# v079 + GEMM loops: the back-to-back s_setprio 0 / s_setprio 1 pair in the middle of each 32-MFMA block removed
# speedup vs baseline: 1.0031x; 1.0031x over previous
;     __device__ bool next(int i, Unit& u) const { if (!b.next(i / 3, u)) return false; u.pz = i % 3; return true; }
; #define PG8_STAGE(bufoff, gbase, voff) do { _Pragma("unroll") for (int _i = 0; _i < 2; ++_i) \
;         __builtin_amdgcn_global_load_lds((const gunsigned*)((const gchar*)(gbase) + (voff)[_i]), (LAS unsigned*)(lds + (bufoff) + ldsw + _i * 8192), 16, 0, 0); } while (0)
; #define PG8_LDA(dst, b, h) do { _Pragma("unroll") for (int m = 0; m < 4; ++m) _Pragma("unroll") for (int k = 0; k < 2; ++k) dst[m][k] = *(const LAS bf16x8*)(lds + PG8_SA(b, h) + aoff + m * 2048 + k * 1024); } while (0)
; #define PG8_LDB(dst, b, h) do { _Pragma("unroll") for (int n = 0; n < 2; ++n) _Pragma("unroll") for (int k = 0; k < 2; ++k) dst[n][k] = *(const LAS bf16x8*)(lds + PG8_SB(b, h) + boff + n * 2048 + k * 1024); } while (0)
; #define PG8_WAIT_V(n) asm volatile("s_waitcnt vmcnt(" #n ")" ::: "memory")
; #define PG8_WAIT_L(n) asm volatile("s_waitcnt lgkmcnt(" #n ")" ::: "memory")
; #define PG8_BAR __builtin_amdgcn_s_barrier()
; template <class Epi, class Sched>
; __device__ __forceinline__ void gemm_phase(LAS unsigned char* lds, const int tid, const Gemm g, const Sched& S, const Epi& E) {
;     ...
;         const bool has_next = S.next(ui + 1, nxt);
;         const gchar* nA = has_next ? (const gchar*)g.A + (size_t)nxt.pm * tstep + (size_t)nxt.pz * g.zA : cA;
;         const gchar* nB = has_next ? (const gchar*)g.Bt + (size_t)nxt.pn * tstep + (size_t)nxt.pz * g.zB : cB;
;         for (int t = 0; t < nt; t += 2) {
;             const bool last = (t == nt - 2);
;             const gchar* a1 = cA + (size_t)(t + 1) * kstep;
;             const gchar* a2 = last ? nA : cA + (size_t)(t + 2) * kstep; const gchar* b2 = last ? nB : cB + (size_t)(t + 2) * kstep;
;             const gchar* a3 = a2 + kstep; const gchar* b3 = b2 + kstep;
;             PG8_LDB(B0, 0, 0); PG8_LDB(B1, 0, 1); PG8_SCHED; PG8_LDA(At, 0, 0); PG8_STAGE(PG8_SA(1, 1), a1 + hstep, voffA);
;             PG8_WAIT_V(8); PG8_WAIT_L(0); PG8_BAR; PG8_MMA(0, 0, At, B0); PG8_MMA(0, 1, At, B1); PG8_BAR; PG8_SCHED;
;             PG8_LDA(At, 0, 1); PG8_STAGE(PG8_SB(0, 0), b2, voffB); PG8_STAGE(PG8_SB(0, 1), b2 + hstep, voffB); PG8_STAGE(PG8_SA(0, 0), a2, voffA);
;             PG8_WAIT_V(8); PG8_WAIT_L(0); PG8_BAR; PG8_MMA(1, 0, At, B0); PG8_MMA(1, 1, At, B1); PG8_BAR; PG8_SCHED;
.LBB0_319:
	s_add_u32 vcc_lo, s10, 0x100
	s_addc_u32 vcc_hi, s11, 0
	s_add_i32 s39, 0, 0x10000
	s_cmp_eq_u32 s29, 40
	s_cselect_b32 s75, s21, vcc_hi
	s_cselect_b32 s74, s20, vcc_lo
	s_cselect_b32 s73, s1, s93
	s_cselect_b32 s72, s0, s31
	s_add_i32 s30, 0, 0x14000
	v_add_u32_e32 v142, s39, v174
	v_add_u32_e32 v168, s30, v174
	ds_read_b128 v[130:133], v142
	ds_read_b128 v[134:137], v142 offset:1024
	ds_read_b128 v[138:141], v142 offset:2048
	ds_read_b128 v[142:145], v142 offset:3072
	ds_read_b128 v[146:149], v168
	ds_read_b128 v[150:153], v168 offset:1024
	ds_read_b128 v[164:167], v168 offset:2048
	ds_read_b128 v[168:171], v168 offset:3072
	s_add_i32 m0, s46, 0xc000
	ds_read_b128 v[192:195], v190
	ds_read_b128 v[204:207], v190 offset:1024
	ds_read_b128 v[208:211], v190 offset:2048
	ds_read_b128 v[212:215], v190 offset:3072
	ds_read_b128 v[216:219], v190 offset:4096
	ds_read_b128 v[220:223], v190 offset:5120
	ds_read_b128 v[224:227], v190 offset:6144
	ds_read_b128 v[242:245], v190 offset:7168
	global_load_lds_dwordx4 v162, s[10:11]
	s_add_i32 m0, s46, 0xe000
	s_nop 0
	global_load_lds_dwordx4 v160, s[10:11]
	s_waitcnt vmcnt(8)
	s_waitcnt lgkmcnt(0)
	s_barrier
	s_setprio 1
	v_mfma_f32_16x16x32_bf16 v[126:129], v[130:133], v[192:195], v[126:129]
	v_mfma_f32_16x16x32_bf16 v[122:125], v[138:141], v[192:195], v[122:125]
	v_mfma_f32_16x16x32_bf16 v[110:113], v[130:133], v[208:211], v[110:113]
	v_mfma_f32_16x16x32_bf16 v[106:109], v[138:141], v[208:211], v[106:109]
	v_mfma_f32_16x16x32_bf16 v[94:97], v[130:133], v[216:219], v[94:97]
	v_mfma_f32_16x16x32_bf16 v[90:93], v[138:141], v[216:219], v[90:93]
	v_mfma_f32_16x16x32_bf16 v[78:81], v[130:133], v[224:227], v[78:81]
	v_mfma_f32_16x16x32_bf16 v[74:77], v[138:141], v[224:227], v[74:77]
	v_mfma_f32_16x16x32_bf16 v[126:129], v[134:137], v[204:207], v[126:129]
	v_mfma_f32_16x16x32_bf16 v[122:125], v[142:145], v[204:207], v[122:125]
	v_mfma_f32_16x16x32_bf16 v[110:113], v[134:137], v[212:215], v[110:113]
	v_mfma_f32_16x16x32_bf16 v[106:109], v[142:145], v[212:215], v[106:109]
	v_mfma_f32_16x16x32_bf16 v[94:97], v[134:137], v[220:223], v[94:97]
	v_mfma_f32_16x16x32_bf16 v[90:93], v[142:145], v[220:223], v[90:93]
	v_mfma_f32_16x16x32_bf16 v[78:81], v[134:137], v[242:245], v[78:81]
	v_mfma_f32_16x16x32_bf16 v[74:77], v[142:145], v[242:245], v[74:77]
	v_mfma_f32_16x16x32_bf16 v[118:121], v[146:149], v[192:195], v[118:121]
	v_mfma_f32_16x16x32_bf16 v[114:117], v[164:167], v[192:195], v[114:117]
	v_mfma_f32_16x16x32_bf16 v[102:105], v[146:149], v[208:211], v[102:105]
	v_mfma_f32_16x16x32_bf16 v[98:101], v[164:167], v[208:211], v[98:101]
	v_mfma_f32_16x16x32_bf16 v[86:89], v[146:149], v[216:219], v[86:89]
	v_mfma_f32_16x16x32_bf16 v[82:85], v[164:167], v[216:219], v[82:85]
	v_mfma_f32_16x16x32_bf16 v[70:73], v[146:149], v[224:227], v[70:73]
	v_mfma_f32_16x16x32_bf16 v[66:69], v[164:167], v[224:227], v[66:69]
	v_mfma_f32_16x16x32_bf16 v[118:121], v[150:153], v[204:207], v[118:121]
	v_mfma_f32_16x16x32_bf16 v[114:117], v[168:171], v[204:207], v[114:117]
	v_mfma_f32_16x16x32_bf16 v[102:105], v[150:153], v[212:215], v[102:105]
	v_mfma_f32_16x16x32_bf16 v[98:101], v[168:171], v[212:215], v[98:101]
	v_mfma_f32_16x16x32_bf16 v[86:89], v[150:153], v[220:223], v[86:89]
	v_mfma_f32_16x16x32_bf16 v[82:85], v[168:171], v[220:223], v[82:85]
	v_mfma_f32_16x16x32_bf16 v[70:73], v[150:153], v[242:245], v[70:73]
	v_mfma_f32_16x16x32_bf16 v[66:69], v[168:171], v[242:245], v[66:69]
	s_barrier
	s_setprio 0
	s_add_i32 s10, s39, s43
	s_mov_b32 m0, s10
	ds_read_b128 v[192:195], v190 offset:16384
	ds_read_b128 v[204:207], v190 offset:17408
	ds_read_b128 v[208:211], v190 offset:18432
	ds_read_b128 v[212:215], v190 offset:19456
	ds_read_b128 v[216:219], v190 offset:20480
	ds_read_b128 v[220:223], v190 offset:21504
	ds_read_b128 v[224:227], v190 offset:22528
	ds_read_b128 v[242:245], v190 offset:23552
	global_load_lds_dwordx4 v0, s[72:73]
	s_add_i32 m0, s10, 0x2000
	s_add_u32 s10, s72, 0xb0000
	s_addc_u32 s11, s73, 0
	s_add_i32 s30, s30, s43
	global_load_lds_dwordx4 v158, s[72:73]
	s_mov_b32 m0, s30
	s_nop 0
	global_load_lds_dwordx4 v0, s[10:11]
	s_add_i32 m0, s30, 0x2000
	s_nop 0
	global_load_lds_dwordx4 v158, s[10:11]
	s_mov_b32 m0, s46
	s_nop 0
	global_load_lds_dwordx4 v154, s[74:75]
	s_mov_b32 m0, s47
	s_nop 0
	global_load_lds_dwordx4 v156, s[74:75]
	s_waitcnt vmcnt(8)
	s_waitcnt lgkmcnt(0)
	s_barrier
	s_setprio 1
	v_mfma_f32_16x16x32_bf16 v[62:65], v[130:133], v[192:195], v[62:65]
	v_mfma_f32_16x16x32_bf16 v[58:61], v[138:141], v[192:195], v[58:61]
	v_mfma_f32_16x16x32_bf16 v[46:49], v[130:133], v[208:211], v[46:49]
	v_mfma_f32_16x16x32_bf16 v[42:45], v[138:141], v[208:211], v[42:45]
	v_mfma_f32_16x16x32_bf16 v[30:33], v[130:133], v[216:219], v[30:33]
	v_mfma_f32_16x16x32_bf16 v[26:29], v[138:141], v[216:219], v[26:29]
	v_mfma_f32_16x16x32_bf16 v[14:17], v[130:133], v[224:227], v[14:17]
	v_mfma_f32_16x16x32_bf16 v[10:13], v[138:141], v[224:227], v[10:13]
	v_mfma_f32_16x16x32_bf16 v[62:65], v[134:137], v[204:207], v[62:65]
	v_mfma_f32_16x16x32_bf16 v[58:61], v[142:145], v[204:207], v[58:61]
	v_mfma_f32_16x16x32_bf16 v[46:49], v[134:137], v[212:215], v[46:49]
	v_mfma_f32_16x16x32_bf16 v[42:45], v[142:145], v[212:215], v[42:45]
	v_mfma_f32_16x16x32_bf16 v[30:33], v[134:137], v[220:223], v[30:33]
	v_mfma_f32_16x16x32_bf16 v[26:29], v[142:145], v[220:223], v[26:29]
	v_mfma_f32_16x16x32_bf16 v[14:17], v[134:137], v[242:245], v[14:17]
	v_mfma_f32_16x16x32_bf16 v[10:13], v[142:145], v[242:245], v[10:13]
	v_mfma_f32_16x16x32_bf16 v[54:57], v[146:149], v[192:195], v[54:57]
	v_mfma_f32_16x16x32_bf16 v[50:53], v[164:167], v[192:195], v[50:53]
	v_mfma_f32_16x16x32_bf16 v[38:41], v[146:149], v[208:211], v[38:41]
	v_mfma_f32_16x16x32_bf16 v[34:37], v[164:167], v[208:211], v[34:37]
	v_mfma_f32_16x16x32_bf16 v[22:25], v[146:149], v[216:219], v[22:25]
	v_mfma_f32_16x16x32_bf16 v[18:21], v[164:167], v[216:219], v[18:21]
	v_mfma_f32_16x16x32_bf16 v[6:9], v[146:149], v[224:227], v[6:9]
	v_mfma_f32_16x16x32_bf16 v[2:5], v[164:167], v[224:227], v[2:5]
	v_mfma_f32_16x16x32_bf16 v[54:57], v[150:153], v[204:207], v[54:57]
	v_mfma_f32_16x16x32_bf16 v[50:53], v[168:171], v[204:207], v[50:53]
	v_mfma_f32_16x16x32_bf16 v[38:41], v[150:153], v[212:215], v[38:41]
	v_mfma_f32_16x16x32_bf16 v[34:37], v[168:171], v[212:215], v[34:37]
	v_mfma_f32_16x16x32_bf16 v[22:25], v[150:153], v[220:223], v[22:25]
	v_mfma_f32_16x16x32_bf16 v[18:21], v[168:171], v[220:223], v[18:21]
	v_mfma_f32_16x16x32_bf16 v[6:9], v[150:153], v[242:245], v[6:9]
	v_mfma_f32_16x16x32_bf16 v[2:5], v[168:171], v[242:245], v[2:5]
	s_barrier
; #define PG8_STAGE(bufoff, gbase, voff) do { _Pragma("unroll") for (int _i = 0; _i < 2; ++_i) \
;         __builtin_amdgcn_global_load_lds((const gunsigned*)((const gchar*)(gbase) + (voff)[_i]), (LAS unsigned*)(lds + (bufoff) + ldsw + _i * 8192), 16, 0, 0); } while (0)
; #define PG8_LDA(dst, b, h) do { _Pragma("unroll") for (int m = 0; m < 4; ++m) _Pragma("unroll") for (int k = 0; k < 2; ++k) dst[m][k] = *(const LAS bf16x8*)(lds + PG8_SA(b, h) + aoff + m * 2048 + k * 1024); } while (0)
; #define PG8_LDB(dst, b, h) do { _Pragma("unroll") for (int n = 0; n < 2; ++n) _Pragma("unroll") for (int k = 0; k < 2; ++k) dst[n][k] = *(const LAS bf16x8*)(lds + PG8_SB(b, h) + boff + n * 2048 + k * 1024); } while (0)
; #define PG8_MMA(ai, bj, At, Bt) do { __builtin_amdgcn_s_setprio(1); _Pragma("unroll") for (int m = 0; m < 4; ++m) _Pragma("unroll") for (int n = 0; n < 2; ++n) _Pragma("unroll") for (int k = 0; k < 2; ++k) \
;         acc[ai][bj][m][n] = __builtin_amdgcn_mfma_f32_16x16x32_bf16(Bt[n][k], At[m][k], acc[ai][bj][m][n], 0, 0, 0); __builtin_amdgcn_s_setprio(0); } while (0)
; #define PG8_WAIT_V(n) asm volatile("s_waitcnt vmcnt(" #n ")" ::: "memory")
; #define PG8_WAIT_L(n) asm volatile("s_waitcnt lgkmcnt(" #n ")" ::: "memory")
; #define PG8_BAR __builtin_amdgcn_s_barrier()
; #define PG8_SCHED __builtin_amdgcn_sched_barrier(0)
; template <class Epi, class Sched>
; __device__ __forceinline__ void gemm_phase(LAS unsigned char* lds, const int tid, const Gemm g, const Sched& S, const Epi& E) {
;     ...
;             PG8_LDB(B0, 1, 0); PG8_LDB(B1, 1, 1); PG8_SCHED; PG8_LDA(At, 1, 0); PG8_STAGE(PG8_SA(0, 1), a2 + hstep, voffA);
;             PG8_WAIT_V(8); PG8_WAIT_L(0); PG8_BAR; PG8_MMA(0, 0, At, B0); PG8_MMA(0, 1, At, B1); PG8_BAR; PG8_SCHED;
;             PG8_LDA(At, 1, 1); PG8_STAGE(PG8_SB(1, 0), b3, voffB); PG8_STAGE(PG8_SB(1, 1), b3 + hstep, voffB); PG8_STAGE(PG8_SA(1, 0), a3, voffA);
;             PG8_WAIT_V(8); PG8_WAIT_L(0); PG8_BAR; PG8_MMA(1, 0, At, B0); PG8_MMA(1, 1, At, B1); PG8_BAR; PG8_SCHED;
;         }
	s_setprio 0
	s_add_i32 s30, 0, 0x18000
	s_add_i32 s39, 0, 0x1c000
	v_add_u32_e32 v142, s30, v174
	v_add_u32_e32 v168, s39, v174
	ds_read_b128 v[130:133], v142
	ds_read_b128 v[134:137], v142 offset:1024
	ds_read_b128 v[138:141], v142 offset:2048
	ds_read_b128 v[142:145], v142 offset:3072
	ds_read_b128 v[146:149], v168
	ds_read_b128 v[150:153], v168 offset:1024
	ds_read_b128 v[164:167], v168 offset:2048
	ds_read_b128 v[168:171], v168 offset:3072
	s_add_u32 s10, s74, 0xb0000
	s_addc_u32 s11, s75, 0
	s_mov_b32 m0, s48
	ds_read_b128 v[192:195], v190 offset:32768
	ds_read_b128 v[204:207], v190 offset:33792
	ds_read_b128 v[208:211], v190 offset:34816
	ds_read_b128 v[212:215], v190 offset:35840
	ds_read_b128 v[216:219], v190 offset:36864
	ds_read_b128 v[220:223], v190 offset:37888
	ds_read_b128 v[224:227], v190 offset:38912
	ds_read_b128 v[242:245], v190 offset:39936
	global_load_lds_dwordx4 v154, s[10:11]
	s_mov_b32 m0, s49
	s_nop 0
	global_load_lds_dwordx4 v156, s[10:11]
	s_waitcnt vmcnt(8)
	s_waitcnt lgkmcnt(0)
	s_barrier
	s_setprio 1
	v_mfma_f32_16x16x32_bf16 v[126:129], v[130:133], v[192:195], v[126:129]
	v_mfma_f32_16x16x32_bf16 v[122:125], v[138:141], v[192:195], v[122:125]
	v_mfma_f32_16x16x32_bf16 v[110:113], v[130:133], v[208:211], v[110:113]
	v_mfma_f32_16x16x32_bf16 v[106:109], v[138:141], v[208:211], v[106:109]
	v_mfma_f32_16x16x32_bf16 v[94:97], v[130:133], v[216:219], v[94:97]
	v_mfma_f32_16x16x32_bf16 v[90:93], v[138:141], v[216:219], v[90:93]
	v_mfma_f32_16x16x32_bf16 v[78:81], v[130:133], v[224:227], v[78:81]
	v_mfma_f32_16x16x32_bf16 v[74:77], v[138:141], v[224:227], v[74:77]
	v_mfma_f32_16x16x32_bf16 v[126:129], v[134:137], v[204:207], v[126:129]
	v_mfma_f32_16x16x32_bf16 v[122:125], v[142:145], v[204:207], v[122:125]
	v_mfma_f32_16x16x32_bf16 v[110:113], v[134:137], v[212:215], v[110:113]
	v_mfma_f32_16x16x32_bf16 v[106:109], v[142:145], v[212:215], v[106:109]
	v_mfma_f32_16x16x32_bf16 v[94:97], v[134:137], v[220:223], v[94:97]
	v_mfma_f32_16x16x32_bf16 v[90:93], v[142:145], v[220:223], v[90:93]
	v_mfma_f32_16x16x32_bf16 v[78:81], v[134:137], v[242:245], v[78:81]
	v_mfma_f32_16x16x32_bf16 v[74:77], v[142:145], v[242:245], v[74:77]
	v_mfma_f32_16x16x32_bf16 v[118:121], v[146:149], v[192:195], v[118:121]
	v_mfma_f32_16x16x32_bf16 v[114:117], v[164:167], v[192:195], v[114:117]
	v_mfma_f32_16x16x32_bf16 v[102:105], v[146:149], v[208:211], v[102:105]
	v_mfma_f32_16x16x32_bf16 v[98:101], v[164:167], v[208:211], v[98:101]
	v_mfma_f32_16x16x32_bf16 v[86:89], v[146:149], v[216:219], v[86:89]
	v_mfma_f32_16x16x32_bf16 v[82:85], v[164:167], v[216:219], v[82:85]
	v_mfma_f32_16x16x32_bf16 v[70:73], v[146:149], v[224:227], v[70:73]
	v_mfma_f32_16x16x32_bf16 v[66:69], v[164:167], v[224:227], v[66:69]
	v_mfma_f32_16x16x32_bf16 v[118:121], v[150:153], v[204:207], v[118:121]
	v_mfma_f32_16x16x32_bf16 v[114:117], v[168:171], v[204:207], v[114:117]
	v_mfma_f32_16x16x32_bf16 v[102:105], v[150:153], v[212:215], v[102:105]
	v_mfma_f32_16x16x32_bf16 v[98:101], v[168:171], v[212:215], v[98:101]
	v_mfma_f32_16x16x32_bf16 v[86:89], v[150:153], v[220:223], v[86:89]
	v_mfma_f32_16x16x32_bf16 v[82:85], v[168:171], v[220:223], v[82:85]
	v_mfma_f32_16x16x32_bf16 v[70:73], v[150:153], v[242:245], v[70:73]
	v_mfma_f32_16x16x32_bf16 v[66:69], v[168:171], v[242:245], v[66:69]
	s_barrier
	s_setprio 0
	s_add_i32 s10, s30, s43
	s_mov_b32 m0, s10
	ds_read_b128 v[192:195], v190 offset:49152
	ds_read_b128 v[204:207], v190 offset:50176
	ds_read_b128 v[208:211], v190 offset:51200
	ds_read_b128 v[212:215], v190 offset:52224
	ds_read_b128 v[216:219], v190 offset:53248
	ds_read_b128 v[220:223], v190 offset:54272
	ds_read_b128 v[224:227], v190 offset:55296
	ds_read_b128 v[242:245], v190 offset:56320
	global_load_lds_dwordx4 v201, s[72:73]
	s_add_i32 m0, s10, 0x2000
	s_add_u32 s10, s72, 0xb0080
	s_addc_u32 s11, s73, 0
	s_add_i32 s30, s39, s43
	global_load_lds_dwordx4 v247, s[72:73]
	s_mov_b32 m0, s30
	s_nop 0
	global_load_lds_dwordx4 v0, s[10:11]
	s_add_i32 m0, s30, 0x2000
	s_nop 0
	global_load_lds_dwordx4 v158, s[10:11]
	s_mov_b32 m0, s53
	s_nop 0
	global_load_lds_dwordx4 v249, s[74:75]
	s_mov_b32 m0, s54
	s_nop 0
	global_load_lds_dwordx4 v251, s[74:75]
	s_waitcnt vmcnt(8)
	s_waitcnt lgkmcnt(0)
	s_barrier
	s_setprio 1
	v_mfma_f32_16x16x32_bf16 v[62:65], v[130:133], v[192:195], v[62:65]
	v_mfma_f32_16x16x32_bf16 v[58:61], v[138:141], v[192:195], v[58:61]
	v_mfma_f32_16x16x32_bf16 v[46:49], v[130:133], v[208:211], v[46:49]
	v_mfma_f32_16x16x32_bf16 v[42:45], v[138:141], v[208:211], v[42:45]
	v_mfma_f32_16x16x32_bf16 v[30:33], v[130:133], v[216:219], v[30:33]
	v_mfma_f32_16x16x32_bf16 v[26:29], v[138:141], v[216:219], v[26:29]
	v_mfma_f32_16x16x32_bf16 v[14:17], v[130:133], v[224:227], v[14:17]
	v_mfma_f32_16x16x32_bf16 v[10:13], v[138:141], v[224:227], v[10:13]
	v_mfma_f32_16x16x32_bf16 v[62:65], v[134:137], v[204:207], v[62:65]
	v_mfma_f32_16x16x32_bf16 v[58:61], v[142:145], v[204:207], v[58:61]
	v_mfma_f32_16x16x32_bf16 v[46:49], v[134:137], v[212:215], v[46:49]
	v_mfma_f32_16x16x32_bf16 v[42:45], v[142:145], v[212:215], v[42:45]
	v_mfma_f32_16x16x32_bf16 v[30:33], v[134:137], v[220:223], v[30:33]
	v_mfma_f32_16x16x32_bf16 v[26:29], v[142:145], v[220:223], v[26:29]
	v_mfma_f32_16x16x32_bf16 v[14:17], v[134:137], v[242:245], v[14:17]
	v_mfma_f32_16x16x32_bf16 v[10:13], v[142:145], v[242:245], v[10:13]
	v_mfma_f32_16x16x32_bf16 v[54:57], v[146:149], v[192:195], v[54:57]
	v_mfma_f32_16x16x32_bf16 v[50:53], v[164:167], v[192:195], v[50:53]
	v_mfma_f32_16x16x32_bf16 v[38:41], v[146:149], v[208:211], v[38:41]
	v_mfma_f32_16x16x32_bf16 v[34:37], v[164:167], v[208:211], v[34:37]
	v_mfma_f32_16x16x32_bf16 v[22:25], v[146:149], v[216:219], v[22:25]
	v_mfma_f32_16x16x32_bf16 v[18:21], v[164:167], v[216:219], v[18:21]
	v_mfma_f32_16x16x32_bf16 v[6:9], v[146:149], v[224:227], v[6:9]
	v_mfma_f32_16x16x32_bf16 v[2:5], v[164:167], v[224:227], v[2:5]
	v_mfma_f32_16x16x32_bf16 v[54:57], v[150:153], v[204:207], v[54:57]
	v_mfma_f32_16x16x32_bf16 v[50:53], v[168:171], v[204:207], v[50:53]
	v_mfma_f32_16x16x32_bf16 v[38:41], v[150:153], v[212:215], v[38:41]
	v_mfma_f32_16x16x32_bf16 v[34:37], v[168:171], v[212:215], v[34:37]
	v_mfma_f32_16x16x32_bf16 v[22:25], v[150:153], v[220:223], v[22:25]
	v_mfma_f32_16x16x32_bf16 v[18:21], v[168:171], v[220:223], v[18:21]
	v_mfma_f32_16x16x32_bf16 v[6:9], v[150:153], v[242:245], v[6:9]
	v_mfma_f32_16x16x32_bf16 v[2:5], v[168:171], v[242:245], v[2:5]
	s_barrier
	s_setprio 0
	s_add_i32 s29, s29, 2
	s_add_u32 s31, s31, 0x100
	s_addc_u32 s93, s93, 0
	s_cmp_gt_u32 s29, 41
	s_mov_b64 s[10:11], vcc
	s_cbranch_scc0 .LBB0_319
	s_and_b64 vcc, exec, s[16:17]
	s_cbranch_vccz .LBB0_322
	s_barrier

;     __device__ bool next(int i, Unit& u) const { if (!b.next(i / 3, u)) return false; u.pz = i % 3; return true; }
; #define PG8_STAGE(bufoff, gbase, voff) do { _Pragma("unroll") for (int _i = 0; _i < 2; ++_i) \
;         __builtin_amdgcn_global_load_lds((const gunsigned*)((const gchar*)(gbase) + (voff)[_i]), (LAS unsigned*)(lds + (bufoff) + ldsw + _i * 8192), 16, 0, 0); } while (0)
; #define PG8_LDA(dst, b, h) do { _Pragma("unroll") for (int m = 0; m < 4; ++m) _Pragma("unroll") for (int k = 0; k < 2; ++k) dst[m][k] = *(const LAS bf16x8*)(lds + PG8_SA(b, h) + aoff + m * 2048 + k * 1024); } while (0)
; #define PG8_LDB(dst, b, h) do { _Pragma("unroll") for (int n = 0; n < 2; ++n) _Pragma("unroll") for (int k = 0; k < 2; ++k) dst[n][k] = *(const LAS bf16x8*)(lds + PG8_SB(b, h) + boff + n * 2048 + k * 1024); } while (0)
; #define PG8_WAIT_V(n) asm volatile("s_waitcnt vmcnt(" #n ")" ::: "memory")
; #define PG8_WAIT_L(n) asm volatile("s_waitcnt lgkmcnt(" #n ")" ::: "memory")
; #define PG8_BAR __builtin_amdgcn_s_barrier()
; template <class Epi, class Sched>
; __device__ __forceinline__ void gemm_phase(LAS unsigned char* lds, const int tid, const Gemm g, const Sched& S, const Epi& E) {
;     ...
;         const bool has_next = S.next(ui + 1, nxt);
;         const gchar* nA = has_next ? (const gchar*)g.A + (size_t)nxt.pm * tstep + (size_t)nxt.pz * g.zA : cA;
;         const gchar* nB = has_next ? (const gchar*)g.Bt + (size_t)nxt.pn * tstep + (size_t)nxt.pz * g.zB : cB;
;         for (int t = 0; t < nt; t += 2) {
;             const bool last = (t == nt - 2);
;             const gchar* a1 = cA + (size_t)(t + 1) * kstep;
;             const gchar* a2 = last ? nA : cA + (size_t)(t + 2) * kstep; const gchar* b2 = last ? nB : cB + (size_t)(t + 2) * kstep;
;             const gchar* a3 = a2 + kstep; const gchar* b3 = b2 + kstep;
;             PG8_LDB(B0, 0, 0); PG8_LDB(B1, 0, 1); PG8_SCHED; PG8_LDA(At, 0, 0); PG8_STAGE(PG8_SA(1, 1), a1 + hstep, voffA);
;             PG8_WAIT_V(8); PG8_WAIT_L(0); PG8_BAR; PG8_MMA(0, 0, At, B0); PG8_MMA(0, 1, At, B1); PG8_BAR; PG8_SCHED;
;             PG8_LDA(At, 0, 1); PG8_STAGE(PG8_SB(0, 0), b2, voffB); PG8_STAGE(PG8_SB(0, 1), b2 + hstep, voffB); PG8_STAGE(PG8_SA(0, 0), a2, voffA);
;             PG8_WAIT_V(8); PG8_WAIT_L(0); PG8_BAR; PG8_MMA(1, 0, At, B0); PG8_MMA(1, 1, At, B1); PG8_BAR; PG8_SCHED;
.LBB0_369:
	s_add_u32 s20, s16, 0xfffc0080
	s_addc_u32 s21, s17, -1
	s_add_i32 s29, 0, 0x10000
	s_cmp_eq_u32 s31, 12
	s_cselect_b32 s57, s11, s21
	s_cselect_b32 s56, s12, s20
	v_add_u32_e32 v140, s29, v145
	s_cselect_b32 s21, s9, s24
	s_cselect_b32 s20, s15, s23
	s_add_i32 s30, 0, 0x14000
	ds_read_b128 v[146:149], v140
	ds_read_b128 v[156:159], v140 offset:1024
	ds_read_b128 v[160:163], v140 offset:2048
	ds_read_b128 v[164:167], v140 offset:3072
	v_add_u32_e32 v140, s30, v145
	ds_read_b128 v[168:171], v140
	ds_read_b128 v[172:175], v140 offset:1024
	ds_read_b128 v[176:179], v140 offset:2048
	ds_read_b128 v[180:183], v140 offset:3072
	s_add_i32 m0, s73, 0xc000
	ds_read_b128 v[184:187], v155
	ds_read_b128 v[188:191], v155 offset:1024
	ds_read_b128 v[192:195], v155 offset:2048
	ds_read_b128 v[204:207], v155 offset:3072
	ds_read_b128 v[208:211], v155 offset:4096
	ds_read_b128 v[212:215], v155 offset:5120
	ds_read_b128 v[216:219], v155 offset:6144
	ds_read_b128 v[220:223], v155 offset:7168
	global_load_lds_dwordx4 v138, s[16:17]
	s_add_i32 m0, s73, 0xe000
	s_nop 0
	global_load_lds_dwordx4 v136, s[16:17]
	s_waitcnt vmcnt(8)
	s_waitcnt lgkmcnt(0)
	s_barrier
	s_setprio 1
	v_mfma_f32_16x16x32_bf16 v[126:129], v[146:149], v[184:187], v[126:129]
	v_mfma_f32_16x16x32_bf16 v[118:121], v[160:163], v[184:187], v[118:121]
	v_mfma_f32_16x16x32_bf16 v[110:113], v[146:149], v[192:195], v[110:113]
	v_mfma_f32_16x16x32_bf16 v[102:105], v[160:163], v[192:195], v[102:105]
	v_mfma_f32_16x16x32_bf16 v[94:97], v[146:149], v[208:211], v[94:97]
	v_mfma_f32_16x16x32_bf16 v[86:89], v[160:163], v[208:211], v[86:89]
	v_mfma_f32_16x16x32_bf16 v[78:81], v[146:149], v[216:219], v[78:81]
	v_mfma_f32_16x16x32_bf16 v[70:73], v[160:163], v[216:219], v[70:73]
	v_mfma_f32_16x16x32_bf16 v[126:129], v[156:159], v[188:191], v[126:129]
	v_mfma_f32_16x16x32_bf16 v[118:121], v[164:167], v[188:191], v[118:121]
	v_mfma_f32_16x16x32_bf16 v[110:113], v[156:159], v[204:207], v[110:113]
	v_mfma_f32_16x16x32_bf16 v[102:105], v[164:167], v[204:207], v[102:105]
	v_mfma_f32_16x16x32_bf16 v[94:97], v[156:159], v[212:215], v[94:97]
	v_mfma_f32_16x16x32_bf16 v[86:89], v[164:167], v[212:215], v[86:89]
	v_mfma_f32_16x16x32_bf16 v[78:81], v[156:159], v[220:223], v[78:81]
	v_mfma_f32_16x16x32_bf16 v[70:73], v[164:167], v[220:223], v[70:73]
	v_mfma_f32_16x16x32_bf16 v[122:125], v[168:171], v[184:187], v[122:125]
	v_mfma_f32_16x16x32_bf16 v[114:117], v[176:179], v[184:187], v[114:117]
	v_mfma_f32_16x16x32_bf16 v[106:109], v[168:171], v[192:195], v[106:109]
	v_mfma_f32_16x16x32_bf16 v[98:101], v[176:179], v[192:195], v[98:101]
	v_mfma_f32_16x16x32_bf16 v[90:93], v[168:171], v[208:211], v[90:93]
	v_mfma_f32_16x16x32_bf16 v[82:85], v[176:179], v[208:211], v[82:85]
	v_mfma_f32_16x16x32_bf16 v[74:77], v[168:171], v[216:219], v[74:77]
	v_mfma_f32_16x16x32_bf16 v[66:69], v[176:179], v[216:219], v[66:69]
	v_mfma_f32_16x16x32_bf16 v[122:125], v[172:175], v[188:191], v[122:125]
	v_mfma_f32_16x16x32_bf16 v[114:117], v[180:183], v[188:191], v[114:117]
	v_mfma_f32_16x16x32_bf16 v[106:109], v[172:175], v[204:207], v[106:109]
	v_mfma_f32_16x16x32_bf16 v[98:101], v[180:183], v[204:207], v[98:101]
	v_mfma_f32_16x16x32_bf16 v[90:93], v[172:175], v[212:215], v[90:93]
	v_mfma_f32_16x16x32_bf16 v[82:85], v[180:183], v[212:215], v[82:85]
	v_mfma_f32_16x16x32_bf16 v[74:77], v[172:175], v[220:223], v[74:77]
	v_mfma_f32_16x16x32_bf16 v[66:69], v[180:183], v[220:223], v[66:69]
	s_barrier
	s_setprio 0
	s_add_i32 s29, s29, s43
	s_mov_b32 m0, s29
	ds_read_b128 v[184:187], v155 offset:16384
	ds_read_b128 v[188:191], v155 offset:17408
	ds_read_b128 v[192:195], v155 offset:18432
	ds_read_b128 v[204:207], v155 offset:19456
	ds_read_b128 v[208:211], v155 offset:20480
	ds_read_b128 v[212:215], v155 offset:21504
	ds_read_b128 v[216:219], v155 offset:22528
	ds_read_b128 v[220:223], v155 offset:23552
	global_load_lds_dwordx4 v0, s[20:21]
	s_add_i32 m0, s29, 0x2000
	s_add_u32 s46, s20, 0x40000
	s_addc_u32 s47, s21, 0
	s_add_i32 s29, s30, s43
	global_load_lds_dwordx4 v130, s[20:21]
	s_mov_b32 m0, s29
	s_nop 0
	global_load_lds_dwordx4 v0, s[46:47]
	s_add_i32 m0, s29, 0x2000
	s_nop 0
	global_load_lds_dwordx4 v130, s[46:47]
	s_mov_b32 m0, s73
	s_nop 0
	global_load_lds_dwordx4 v134, s[56:57]
	s_mov_b32 m0, s74
	s_nop 0
	global_load_lds_dwordx4 v132, s[56:57]
	s_waitcnt vmcnt(8)
	s_waitcnt lgkmcnt(0)
	s_barrier
	s_setprio 1
	v_mfma_f32_16x16x32_bf16 v[62:65], v[146:149], v[184:187], v[62:65]
	v_mfma_f32_16x16x32_bf16 v[54:57], v[160:163], v[184:187], v[54:57]
	v_mfma_f32_16x16x32_bf16 v[46:49], v[146:149], v[192:195], v[46:49]
	v_mfma_f32_16x16x32_bf16 v[38:41], v[160:163], v[192:195], v[38:41]
	v_mfma_f32_16x16x32_bf16 v[30:33], v[146:149], v[208:211], v[30:33]
	v_mfma_f32_16x16x32_bf16 v[22:25], v[160:163], v[208:211], v[22:25]
	v_mfma_f32_16x16x32_bf16 v[14:17], v[146:149], v[216:219], v[14:17]
	v_mfma_f32_16x16x32_bf16 v[6:9], v[160:163], v[216:219], v[6:9]
	v_mfma_f32_16x16x32_bf16 v[62:65], v[156:159], v[188:191], v[62:65]
	v_mfma_f32_16x16x32_bf16 v[54:57], v[164:167], v[188:191], v[54:57]
	v_mfma_f32_16x16x32_bf16 v[46:49], v[156:159], v[204:207], v[46:49]
	v_mfma_f32_16x16x32_bf16 v[38:41], v[164:167], v[204:207], v[38:41]
	v_mfma_f32_16x16x32_bf16 v[30:33], v[156:159], v[212:215], v[30:33]
	v_mfma_f32_16x16x32_bf16 v[22:25], v[164:167], v[212:215], v[22:25]
	v_mfma_f32_16x16x32_bf16 v[14:17], v[156:159], v[220:223], v[14:17]
	v_mfma_f32_16x16x32_bf16 v[6:9], v[164:167], v[220:223], v[6:9]
	v_mfma_f32_16x16x32_bf16 v[58:61], v[168:171], v[184:187], v[58:61]
	v_mfma_f32_16x16x32_bf16 v[50:53], v[176:179], v[184:187], v[50:53]
	v_mfma_f32_16x16x32_bf16 v[42:45], v[168:171], v[192:195], v[42:45]
	v_mfma_f32_16x16x32_bf16 v[34:37], v[176:179], v[192:195], v[34:37]
	v_mfma_f32_16x16x32_bf16 v[26:29], v[168:171], v[208:211], v[26:29]
	v_mfma_f32_16x16x32_bf16 v[18:21], v[176:179], v[208:211], v[18:21]
	v_mfma_f32_16x16x32_bf16 v[10:13], v[168:171], v[216:219], v[10:13]
	v_mfma_f32_16x16x32_bf16 v[2:5], v[176:179], v[216:219], v[2:5]
	v_mfma_f32_16x16x32_bf16 v[58:61], v[172:175], v[188:191], v[58:61]
	v_mfma_f32_16x16x32_bf16 v[50:53], v[180:183], v[188:191], v[50:53]
	v_mfma_f32_16x16x32_bf16 v[42:45], v[172:175], v[204:207], v[42:45]
	v_mfma_f32_16x16x32_bf16 v[34:37], v[180:183], v[204:207], v[34:37]
	v_mfma_f32_16x16x32_bf16 v[26:29], v[172:175], v[212:215], v[26:29]
	v_mfma_f32_16x16x32_bf16 v[18:21], v[180:183], v[212:215], v[18:21]
	v_mfma_f32_16x16x32_bf16 v[10:13], v[172:175], v[220:223], v[10:13]
	v_mfma_f32_16x16x32_bf16 v[2:5], v[180:183], v[220:223], v[2:5]
	s_barrier
; #define PG8_STAGE(bufoff, gbase, voff) do { _Pragma("unroll") for (int _i = 0; _i < 2; ++_i) \
;         __builtin_amdgcn_global_load_lds((const gunsigned*)((const gchar*)(gbase) + (voff)[_i]), (LAS unsigned*)(lds + (bufoff) + ldsw + _i * 8192), 16, 0, 0); } while (0)
; #define PG8_LDA(dst, b, h) do { _Pragma("unroll") for (int m = 0; m < 4; ++m) _Pragma("unroll") for (int k = 0; k < 2; ++k) dst[m][k] = *(const LAS bf16x8*)(lds + PG8_SA(b, h) + aoff + m * 2048 + k * 1024); } while (0)
; #define PG8_LDB(dst, b, h) do { _Pragma("unroll") for (int n = 0; n < 2; ++n) _Pragma("unroll") for (int k = 0; k < 2; ++k) dst[n][k] = *(const LAS bf16x8*)(lds + PG8_SB(b, h) + boff + n * 2048 + k * 1024); } while (0)
; #define PG8_MMA(ai, bj, At, Bt) do { __builtin_amdgcn_s_setprio(1); _Pragma("unroll") for (int m = 0; m < 4; ++m) _Pragma("unroll") for (int n = 0; n < 2; ++n) _Pragma("unroll") for (int k = 0; k < 2; ++k) \
;         acc[ai][bj][m][n] = __builtin_amdgcn_mfma_f32_16x16x32_bf16(Bt[n][k], At[m][k], acc[ai][bj][m][n], 0, 0, 0); __builtin_amdgcn_s_setprio(0); } while (0)
; #define PG8_WAIT_V(n) asm volatile("s_waitcnt vmcnt(" #n ")" ::: "memory")
; #define PG8_WAIT_L(n) asm volatile("s_waitcnt lgkmcnt(" #n ")" ::: "memory")
; #define PG8_BAR __builtin_amdgcn_s_barrier()
; #define PG8_SCHED __builtin_amdgcn_sched_barrier(0)
; template <class Epi, class Sched>
; __device__ __forceinline__ void gemm_phase(LAS unsigned char* lds, const int tid, const Gemm g, const Sched& S, const Epi& E) {
;     ...
;             PG8_LDB(B0, 1, 0); PG8_LDB(B1, 1, 1); PG8_SCHED; PG8_LDA(At, 1, 0); PG8_STAGE(PG8_SA(0, 1), a2 + hstep, voffA);
;             PG8_WAIT_V(8); PG8_WAIT_L(0); PG8_BAR; PG8_MMA(0, 0, At, B0); PG8_MMA(0, 1, At, B1); PG8_BAR; PG8_SCHED;
;             PG8_LDA(At, 1, 1); PG8_STAGE(PG8_SB(1, 0), b3, voffB); PG8_STAGE(PG8_SB(1, 1), b3 + hstep, voffB); PG8_STAGE(PG8_SA(1, 0), a3, voffA);
;             PG8_WAIT_V(8); PG8_WAIT_L(0); PG8_BAR; PG8_MMA(1, 0, At, B0); PG8_MMA(1, 1, At, B1); PG8_BAR; PG8_SCHED;
;         }
	s_setprio 0
	s_add_i32 s29, 0, 0x18000
	v_add_u32_e32 v142, s29, v145
	s_add_i32 s30, 0, 0x1c000
	ds_read_b128 v[146:149], v142
	ds_read_b128 v[156:159], v142 offset:1024
	ds_read_b128 v[160:163], v142 offset:2048
	ds_read_b128 v[164:167], v142 offset:3072
	v_add_u32_e32 v142, s30, v145
	ds_read_b128 v[168:171], v142
	ds_read_b128 v[172:175], v142 offset:1024
	ds_read_b128 v[176:179], v142 offset:2048
	ds_read_b128 v[180:183], v142 offset:3072
	s_add_u32 s46, s56, 0x40000
	s_addc_u32 s47, s57, 0
	s_mov_b32 m0, s75
	ds_read_b128 v[184:187], v155 offset:32768
	ds_read_b128 v[188:191], v155 offset:33792
	ds_read_b128 v[192:195], v155 offset:34816
	ds_read_b128 v[204:207], v155 offset:35840
	ds_read_b128 v[208:211], v155 offset:36864
	ds_read_b128 v[212:215], v155 offset:37888
	ds_read_b128 v[216:219], v155 offset:38912
	ds_read_b128 v[220:223], v155 offset:39936
	global_load_lds_dwordx4 v134, s[46:47]
	s_mov_b32 m0, s92
	s_nop 0
	global_load_lds_dwordx4 v132, s[46:47]
	s_waitcnt vmcnt(8)
	s_waitcnt lgkmcnt(0)
	s_barrier
	s_setprio 1
	v_mfma_f32_16x16x32_bf16 v[126:129], v[146:149], v[184:187], v[126:129]
	v_mfma_f32_16x16x32_bf16 v[118:121], v[160:163], v[184:187], v[118:121]
	v_mfma_f32_16x16x32_bf16 v[110:113], v[146:149], v[192:195], v[110:113]
	v_mfma_f32_16x16x32_bf16 v[102:105], v[160:163], v[192:195], v[102:105]
	v_mfma_f32_16x16x32_bf16 v[94:97], v[146:149], v[208:211], v[94:97]
	v_mfma_f32_16x16x32_bf16 v[86:89], v[160:163], v[208:211], v[86:89]
	v_mfma_f32_16x16x32_bf16 v[78:81], v[146:149], v[216:219], v[78:81]
	v_mfma_f32_16x16x32_bf16 v[70:73], v[160:163], v[216:219], v[70:73]
	v_mfma_f32_16x16x32_bf16 v[126:129], v[156:159], v[188:191], v[126:129]
	v_mfma_f32_16x16x32_bf16 v[118:121], v[164:167], v[188:191], v[118:121]
	v_mfma_f32_16x16x32_bf16 v[110:113], v[156:159], v[204:207], v[110:113]
	v_mfma_f32_16x16x32_bf16 v[102:105], v[164:167], v[204:207], v[102:105]
	v_mfma_f32_16x16x32_bf16 v[94:97], v[156:159], v[212:215], v[94:97]
	v_mfma_f32_16x16x32_bf16 v[86:89], v[164:167], v[212:215], v[86:89]
	v_mfma_f32_16x16x32_bf16 v[78:81], v[156:159], v[220:223], v[78:81]
	v_mfma_f32_16x16x32_bf16 v[70:73], v[164:167], v[220:223], v[70:73]
	v_mfma_f32_16x16x32_bf16 v[122:125], v[168:171], v[184:187], v[122:125]
	v_mfma_f32_16x16x32_bf16 v[114:117], v[176:179], v[184:187], v[114:117]
	v_mfma_f32_16x16x32_bf16 v[106:109], v[168:171], v[192:195], v[106:109]
	v_mfma_f32_16x16x32_bf16 v[98:101], v[176:179], v[192:195], v[98:101]
	v_mfma_f32_16x16x32_bf16 v[90:93], v[168:171], v[208:211], v[90:93]
	v_mfma_f32_16x16x32_bf16 v[82:85], v[176:179], v[208:211], v[82:85]
	v_mfma_f32_16x16x32_bf16 v[74:77], v[168:171], v[216:219], v[74:77]
	v_mfma_f32_16x16x32_bf16 v[66:69], v[176:179], v[216:219], v[66:69]
	v_mfma_f32_16x16x32_bf16 v[122:125], v[172:175], v[188:191], v[122:125]
	v_mfma_f32_16x16x32_bf16 v[114:117], v[180:183], v[188:191], v[114:117]
	v_mfma_f32_16x16x32_bf16 v[106:109], v[172:175], v[204:207], v[106:109]
	v_mfma_f32_16x16x32_bf16 v[98:101], v[180:183], v[204:207], v[98:101]
	v_mfma_f32_16x16x32_bf16 v[90:93], v[172:175], v[212:215], v[90:93]
	v_mfma_f32_16x16x32_bf16 v[82:85], v[180:183], v[212:215], v[82:85]
	v_mfma_f32_16x16x32_bf16 v[74:77], v[172:175], v[220:223], v[74:77]
	v_mfma_f32_16x16x32_bf16 v[66:69], v[180:183], v[220:223], v[66:69]
	s_barrier
	s_setprio 0
	s_add_i32 s29, s29, s43
	s_mov_b32 m0, s29
	ds_read_b128 v[184:187], v155 offset:49152
	ds_read_b128 v[188:191], v155 offset:50176
	ds_read_b128 v[192:195], v155 offset:51200
	ds_read_b128 v[204:207], v155 offset:52224
	ds_read_b128 v[208:211], v155 offset:53248
	ds_read_b128 v[212:215], v155 offset:54272
	ds_read_b128 v[216:219], v155 offset:55296
	ds_read_b128 v[220:223], v155 offset:56320
	global_load_lds_dwordx4 v141, s[20:21]
	s_add_i32 m0, s29, 0x2000
	s_add_i32 s29, s30, s43
	global_load_lds_dwordx4 v153, s[20:21]
	s_add_u32 s20, s20, 0x40080
	s_addc_u32 s21, s21, 0
	s_mov_b32 m0, s29
	s_nop 0
	global_load_lds_dwordx4 v0, s[20:21]
	s_add_i32 m0, s29, 0x2000
	s_nop 0
	global_load_lds_dwordx4 v130, s[20:21]
	s_mov_b32 m0, s93
	s_nop 0
	global_load_lds_dwordx4 v201, s[56:57]
	s_mov_b32 m0, s44
	s_nop 0
	global_load_lds_dwordx4 v225, s[56:57]
	s_waitcnt vmcnt(8)
	s_waitcnt lgkmcnt(0)
	s_barrier
	s_setprio 1
	v_mfma_f32_16x16x32_bf16 v[62:65], v[146:149], v[184:187], v[62:65]
	v_mfma_f32_16x16x32_bf16 v[54:57], v[160:163], v[184:187], v[54:57]
	v_mfma_f32_16x16x32_bf16 v[46:49], v[146:149], v[192:195], v[46:49]
	v_mfma_f32_16x16x32_bf16 v[38:41], v[160:163], v[192:195], v[38:41]
	v_mfma_f32_16x16x32_bf16 v[30:33], v[146:149], v[208:211], v[30:33]
	v_mfma_f32_16x16x32_bf16 v[22:25], v[160:163], v[208:211], v[22:25]
	v_mfma_f32_16x16x32_bf16 v[14:17], v[146:149], v[216:219], v[14:17]
	v_mfma_f32_16x16x32_bf16 v[6:9], v[160:163], v[216:219], v[6:9]
	v_mfma_f32_16x16x32_bf16 v[62:65], v[156:159], v[188:191], v[62:65]
	v_mfma_f32_16x16x32_bf16 v[54:57], v[164:167], v[188:191], v[54:57]
	v_mfma_f32_16x16x32_bf16 v[46:49], v[156:159], v[204:207], v[46:49]
	v_mfma_f32_16x16x32_bf16 v[38:41], v[164:167], v[204:207], v[38:41]
	v_mfma_f32_16x16x32_bf16 v[30:33], v[156:159], v[212:215], v[30:33]
	v_mfma_f32_16x16x32_bf16 v[22:25], v[164:167], v[212:215], v[22:25]
	v_mfma_f32_16x16x32_bf16 v[14:17], v[156:159], v[220:223], v[14:17]
	v_mfma_f32_16x16x32_bf16 v[6:9], v[164:167], v[220:223], v[6:9]
	v_mfma_f32_16x16x32_bf16 v[58:61], v[168:171], v[184:187], v[58:61]
	v_mfma_f32_16x16x32_bf16 v[50:53], v[176:179], v[184:187], v[50:53]
	v_mfma_f32_16x16x32_bf16 v[42:45], v[168:171], v[192:195], v[42:45]
	v_mfma_f32_16x16x32_bf16 v[34:37], v[176:179], v[192:195], v[34:37]
	v_mfma_f32_16x16x32_bf16 v[26:29], v[168:171], v[208:211], v[26:29]
	v_mfma_f32_16x16x32_bf16 v[18:21], v[176:179], v[208:211], v[18:21]
	v_mfma_f32_16x16x32_bf16 v[10:13], v[168:171], v[216:219], v[10:13]
	v_mfma_f32_16x16x32_bf16 v[2:5], v[176:179], v[216:219], v[2:5]
	v_mfma_f32_16x16x32_bf16 v[58:61], v[172:175], v[188:191], v[58:61]
	v_mfma_f32_16x16x32_bf16 v[50:53], v[180:183], v[188:191], v[50:53]
	v_mfma_f32_16x16x32_bf16 v[42:45], v[172:175], v[204:207], v[42:45]
	v_mfma_f32_16x16x32_bf16 v[34:37], v[180:183], v[204:207], v[34:37]
	v_mfma_f32_16x16x32_bf16 v[26:29], v[172:175], v[212:215], v[26:29]
	v_mfma_f32_16x16x32_bf16 v[18:21], v[180:183], v[212:215], v[18:21]
	v_mfma_f32_16x16x32_bf16 v[10:13], v[172:175], v[220:223], v[10:13]
	v_mfma_f32_16x16x32_bf16 v[2:5], v[180:183], v[220:223], v[2:5]
	s_barrier
	s_setprio 0
	s_add_i32 s31, s31, 2
	s_add_u32 s23, s23, 0x100
	s_addc_u32 s24, s24, 0
	s_add_u32 s16, s16, 0x100
	s_addc_u32 s17, s17, 0
	s_cmp_gt_u32 s31, 13
	s_cbranch_scc0 .LBB0_369
	s_and_b64 vcc, exec, s[6:7]
	s_cbranch_vccz .LBB0_372
	s_barrier

;     __device__ bool next(int i, Unit& u) const { if (!b.next(i / 3, u)) return false; u.pz = i % 3; return true; }
; #define PG8_STAGE(bufoff, gbase, voff) do { _Pragma("unroll") for (int _i = 0; _i < 2; ++_i) \
;         __builtin_amdgcn_global_load_lds((const gunsigned*)((const gchar*)(gbase) + (voff)[_i]), (LAS unsigned*)(lds + (bufoff) + ldsw + _i * 8192), 16, 0, 0); } while (0)
; #define PG8_LDA(dst, b, h) do { _Pragma("unroll") for (int m = 0; m < 4; ++m) _Pragma("unroll") for (int k = 0; k < 2; ++k) dst[m][k] = *(const LAS bf16x8*)(lds + PG8_SA(b, h) + aoff + m * 2048 + k * 1024); } while (0)
; #define PG8_LDB(dst, b, h) do { _Pragma("unroll") for (int n = 0; n < 2; ++n) _Pragma("unroll") for (int k = 0; k < 2; ++k) dst[n][k] = *(const LAS bf16x8*)(lds + PG8_SB(b, h) + boff + n * 2048 + k * 1024); } while (0)
; #define PG8_WAIT_V(n) asm volatile("s_waitcnt vmcnt(" #n ")" ::: "memory")
; #define PG8_WAIT_L(n) asm volatile("s_waitcnt lgkmcnt(" #n ")" ::: "memory")
; #define PG8_BAR __builtin_amdgcn_s_barrier()
; template <class Epi, class Sched>
; __device__ __forceinline__ void gemm_phase(LAS unsigned char* lds, const int tid, const Gemm g, const Sched& S, const Epi& E) {
;     ...
;         const bool has_next = S.next(ui + 1, nxt);
;         const gchar* nA = has_next ? (const gchar*)g.A + (size_t)nxt.pm * tstep + (size_t)nxt.pz * g.zA : cA;
;         const gchar* nB = has_next ? (const gchar*)g.Bt + (size_t)nxt.pn * tstep + (size_t)nxt.pz * g.zB : cB;
;         for (int t = 0; t < nt; t += 2) {
;             const bool last = (t == nt - 2);
;             const gchar* a1 = cA + (size_t)(t + 1) * kstep;
;             const gchar* a2 = last ? nA : cA + (size_t)(t + 2) * kstep; const gchar* b2 = last ? nB : cB + (size_t)(t + 2) * kstep;
;             const gchar* a3 = a2 + kstep; const gchar* b3 = b2 + kstep;
;             PG8_LDB(B0, 0, 0); PG8_LDB(B1, 0, 1); PG8_SCHED; PG8_LDA(At, 0, 0); PG8_STAGE(PG8_SA(1, 1), a1 + hstep, voffA);
;             PG8_WAIT_V(8); PG8_WAIT_L(0); PG8_BAR; PG8_MMA(0, 0, At, B0); PG8_MMA(0, 1, At, B1); PG8_BAR; PG8_SCHED;
;             PG8_LDA(At, 0, 1); PG8_STAGE(PG8_SB(0, 0), b2, voffB); PG8_STAGE(PG8_SB(0, 1), b2 + hstep, voffB); PG8_STAGE(PG8_SA(0, 0), a2, voffA);
;             PG8_WAIT_V(8); PG8_WAIT_L(0); PG8_BAR; PG8_MMA(1, 0, At, B0); PG8_MMA(1, 1, At, B1); PG8_BAR; PG8_SCHED;
.LBB0_397:
	s_add_u32 s20, s92, 0xfffc0080
	s_addc_u32 s21, s93, -1
	s_add_i32 s29, 0, 0x10000
	s_cmp_eq_u32 s53, 12
	s_cselect_b32 s73, s1, s21
	s_cselect_b32 s72, s31, s20
	s_cselect_b32 s21, s17, s52
	s_cselect_b32 s20, s50, s51
	s_add_i32 s30, 0, 0x14000
	v_add_u32_e32 v142, s29, v177
	v_add_u32_e32 v168, s30, v177
	ds_read_b128 v[130:133], v142
	ds_read_b128 v[134:137], v142 offset:1024
	ds_read_b128 v[138:141], v142 offset:2048
	ds_read_b128 v[142:145], v142 offset:3072
	ds_read_b128 v[146:149], v168
	ds_read_b128 v[150:153], v168 offset:1024
	ds_read_b128 v[164:167], v168 offset:2048
	ds_read_b128 v[168:171], v168 offset:3072
	s_add_i32 m0, s43, 0xc000
	ds_read_b128 v[172:175], v181
	ds_read_b128 v[182:185], v181 offset:1024
	ds_read_b128 v[186:189], v181 offset:2048
	ds_read_b128 v[190:193], v181 offset:3072
	ds_read_b128 v[204:207], v181 offset:4096
	ds_read_b128 v[208:211], v181 offset:5120
	ds_read_b128 v[212:215], v181 offset:6144
	ds_read_b128 v[216:219], v181 offset:7168
	global_load_lds_dwordx4 v162, s[92:93]
	s_add_i32 m0, s43, 0xe000
	s_nop 0
	global_load_lds_dwordx4 v160, s[92:93]
	s_waitcnt vmcnt(8)
	s_waitcnt lgkmcnt(0)
	s_barrier
	s_setprio 1
	v_mfma_f32_16x16x32_bf16 v[126:129], v[130:133], v[172:175], v[126:129]
	v_mfma_f32_16x16x32_bf16 v[122:125], v[138:141], v[172:175], v[122:125]
	v_mfma_f32_16x16x32_bf16 v[110:113], v[130:133], v[186:189], v[110:113]
	v_mfma_f32_16x16x32_bf16 v[106:109], v[138:141], v[186:189], v[106:109]
	v_mfma_f32_16x16x32_bf16 v[94:97], v[130:133], v[204:207], v[94:97]
	v_mfma_f32_16x16x32_bf16 v[90:93], v[138:141], v[204:207], v[90:93]
	v_mfma_f32_16x16x32_bf16 v[78:81], v[130:133], v[212:215], v[78:81]
	v_mfma_f32_16x16x32_bf16 v[74:77], v[138:141], v[212:215], v[74:77]
	v_mfma_f32_16x16x32_bf16 v[126:129], v[134:137], v[182:185], v[126:129]
	v_mfma_f32_16x16x32_bf16 v[122:125], v[142:145], v[182:185], v[122:125]
	v_mfma_f32_16x16x32_bf16 v[110:113], v[134:137], v[190:193], v[110:113]
	v_mfma_f32_16x16x32_bf16 v[106:109], v[142:145], v[190:193], v[106:109]
	v_mfma_f32_16x16x32_bf16 v[94:97], v[134:137], v[208:211], v[94:97]
	v_mfma_f32_16x16x32_bf16 v[90:93], v[142:145], v[208:211], v[90:93]
	v_mfma_f32_16x16x32_bf16 v[78:81], v[134:137], v[216:219], v[78:81]
	v_mfma_f32_16x16x32_bf16 v[74:77], v[142:145], v[216:219], v[74:77]
	v_mfma_f32_16x16x32_bf16 v[118:121], v[146:149], v[172:175], v[118:121]
	v_mfma_f32_16x16x32_bf16 v[114:117], v[164:167], v[172:175], v[114:117]
	v_mfma_f32_16x16x32_bf16 v[102:105], v[146:149], v[186:189], v[102:105]
	v_mfma_f32_16x16x32_bf16 v[98:101], v[164:167], v[186:189], v[98:101]
	v_mfma_f32_16x16x32_bf16 v[86:89], v[146:149], v[204:207], v[86:89]
	v_mfma_f32_16x16x32_bf16 v[82:85], v[164:167], v[204:207], v[82:85]
	v_mfma_f32_16x16x32_bf16 v[70:73], v[146:149], v[212:215], v[70:73]
	v_mfma_f32_16x16x32_bf16 v[66:69], v[164:167], v[212:215], v[66:69]
	v_mfma_f32_16x16x32_bf16 v[118:121], v[150:153], v[182:185], v[118:121]
	v_mfma_f32_16x16x32_bf16 v[114:117], v[168:171], v[182:185], v[114:117]
	v_mfma_f32_16x16x32_bf16 v[102:105], v[150:153], v[190:193], v[102:105]
	v_mfma_f32_16x16x32_bf16 v[98:101], v[168:171], v[190:193], v[98:101]
	v_mfma_f32_16x16x32_bf16 v[86:89], v[150:153], v[208:211], v[86:89]
	v_mfma_f32_16x16x32_bf16 v[82:85], v[168:171], v[208:211], v[82:85]
	v_mfma_f32_16x16x32_bf16 v[70:73], v[150:153], v[216:219], v[70:73]
	v_mfma_f32_16x16x32_bf16 v[66:69], v[168:171], v[216:219], v[66:69]
	s_barrier
	s_setprio 0
	s_add_i32 s29, s29, s15
	s_mov_b32 m0, s29
	ds_read_b128 v[172:175], v181 offset:16384
	ds_read_b128 v[182:185], v181 offset:17408
	ds_read_b128 v[186:189], v181 offset:18432
	ds_read_b128 v[190:193], v181 offset:19456
	ds_read_b128 v[204:207], v181 offset:20480
	ds_read_b128 v[208:211], v181 offset:21504
	ds_read_b128 v[212:215], v181 offset:22528
	ds_read_b128 v[216:219], v181 offset:23552
	global_load_lds_dwordx4 v0, s[20:21]
	s_add_i32 m0, s29, 0x2000
	s_add_u32 s54, s20, 0x40000
	s_addc_u32 s55, s21, 0
	s_add_i32 s29, s30, s15
	global_load_lds_dwordx4 v158, s[20:21]
	s_mov_b32 m0, s29
	s_nop 0
	global_load_lds_dwordx4 v0, s[54:55]
	s_add_i32 m0, s29, 0x2000
	s_nop 0
	global_load_lds_dwordx4 v158, s[54:55]
	s_mov_b32 m0, s43
	s_nop 0
	global_load_lds_dwordx4 v154, s[72:73]
	s_mov_b32 m0, s44
	s_nop 0
	global_load_lds_dwordx4 v156, s[72:73]
	s_waitcnt vmcnt(8)
	s_waitcnt lgkmcnt(0)
	s_barrier
	s_setprio 1
	v_mfma_f32_16x16x32_bf16 v[62:65], v[130:133], v[172:175], v[62:65]
	v_mfma_f32_16x16x32_bf16 v[58:61], v[138:141], v[172:175], v[58:61]
	v_mfma_f32_16x16x32_bf16 v[46:49], v[130:133], v[186:189], v[46:49]
	v_mfma_f32_16x16x32_bf16 v[42:45], v[138:141], v[186:189], v[42:45]
	v_mfma_f32_16x16x32_bf16 v[30:33], v[130:133], v[204:207], v[30:33]
	v_mfma_f32_16x16x32_bf16 v[26:29], v[138:141], v[204:207], v[26:29]
	v_mfma_f32_16x16x32_bf16 v[14:17], v[130:133], v[212:215], v[14:17]
	v_mfma_f32_16x16x32_bf16 v[10:13], v[138:141], v[212:215], v[10:13]
	v_mfma_f32_16x16x32_bf16 v[62:65], v[134:137], v[182:185], v[62:65]
	v_mfma_f32_16x16x32_bf16 v[58:61], v[142:145], v[182:185], v[58:61]
	v_mfma_f32_16x16x32_bf16 v[46:49], v[134:137], v[190:193], v[46:49]
	v_mfma_f32_16x16x32_bf16 v[42:45], v[142:145], v[190:193], v[42:45]
	v_mfma_f32_16x16x32_bf16 v[30:33], v[134:137], v[208:211], v[30:33]
	v_mfma_f32_16x16x32_bf16 v[26:29], v[142:145], v[208:211], v[26:29]
	v_mfma_f32_16x16x32_bf16 v[14:17], v[134:137], v[216:219], v[14:17]
	v_mfma_f32_16x16x32_bf16 v[10:13], v[142:145], v[216:219], v[10:13]
	v_mfma_f32_16x16x32_bf16 v[54:57], v[146:149], v[172:175], v[54:57]
	v_mfma_f32_16x16x32_bf16 v[50:53], v[164:167], v[172:175], v[50:53]
	v_mfma_f32_16x16x32_bf16 v[38:41], v[146:149], v[186:189], v[38:41]
	v_mfma_f32_16x16x32_bf16 v[34:37], v[164:167], v[186:189], v[34:37]
	v_mfma_f32_16x16x32_bf16 v[22:25], v[146:149], v[204:207], v[22:25]
	v_mfma_f32_16x16x32_bf16 v[18:21], v[164:167], v[204:207], v[18:21]
	v_mfma_f32_16x16x32_bf16 v[6:9], v[146:149], v[212:215], v[6:9]
	v_mfma_f32_16x16x32_bf16 v[2:5], v[164:167], v[212:215], v[2:5]
	v_mfma_f32_16x16x32_bf16 v[54:57], v[150:153], v[182:185], v[54:57]
	v_mfma_f32_16x16x32_bf16 v[50:53], v[168:171], v[182:185], v[50:53]
	v_mfma_f32_16x16x32_bf16 v[38:41], v[150:153], v[190:193], v[38:41]
	v_mfma_f32_16x16x32_bf16 v[34:37], v[168:171], v[190:193], v[34:37]
	v_mfma_f32_16x16x32_bf16 v[22:25], v[150:153], v[208:211], v[22:25]
	v_mfma_f32_16x16x32_bf16 v[18:21], v[168:171], v[208:211], v[18:21]
	v_mfma_f32_16x16x32_bf16 v[6:9], v[150:153], v[216:219], v[6:9]
	v_mfma_f32_16x16x32_bf16 v[2:5], v[168:171], v[216:219], v[2:5]
	s_barrier
; #define PG8_STAGE(bufoff, gbase, voff) do { _Pragma("unroll") for (int _i = 0; _i < 2; ++_i) \
;         __builtin_amdgcn_global_load_lds((const gunsigned*)((const gchar*)(gbase) + (voff)[_i]), (LAS unsigned*)(lds + (bufoff) + ldsw + _i * 8192), 16, 0, 0); } while (0)
; #define PG8_LDA(dst, b, h) do { _Pragma("unroll") for (int m = 0; m < 4; ++m) _Pragma("unroll") for (int k = 0; k < 2; ++k) dst[m][k] = *(const LAS bf16x8*)(lds + PG8_SA(b, h) + aoff + m * 2048 + k * 1024); } while (0)
; #define PG8_LDB(dst, b, h) do { _Pragma("unroll") for (int n = 0; n < 2; ++n) _Pragma("unroll") for (int k = 0; k < 2; ++k) dst[n][k] = *(const LAS bf16x8*)(lds + PG8_SB(b, h) + boff + n * 2048 + k * 1024); } while (0)
; #define PG8_MMA(ai, bj, At, Bt) do { __builtin_amdgcn_s_setprio(1); _Pragma("unroll") for (int m = 0; m < 4; ++m) _Pragma("unroll") for (int n = 0; n < 2; ++n) _Pragma("unroll") for (int k = 0; k < 2; ++k) \
;         acc[ai][bj][m][n] = __builtin_amdgcn_mfma_f32_16x16x32_bf16(Bt[n][k], At[m][k], acc[ai][bj][m][n], 0, 0, 0); __builtin_amdgcn_s_setprio(0); } while (0)
; #define PG8_WAIT_V(n) asm volatile("s_waitcnt vmcnt(" #n ")" ::: "memory")
; #define PG8_WAIT_L(n) asm volatile("s_waitcnt lgkmcnt(" #n ")" ::: "memory")
; #define PG8_BAR __builtin_amdgcn_s_barrier()
; #define PG8_SCHED __builtin_amdgcn_sched_barrier(0)
; template <class Epi, class Sched>
; __device__ __forceinline__ void gemm_phase(LAS unsigned char* lds, const int tid, const Gemm g, const Sched& S, const Epi& E) {
;     ...
;             PG8_LDB(B0, 1, 0); PG8_LDB(B1, 1, 1); PG8_SCHED; PG8_LDA(At, 1, 0); PG8_STAGE(PG8_SA(0, 1), a2 + hstep, voffA);
;             PG8_WAIT_V(8); PG8_WAIT_L(0); PG8_BAR; PG8_MMA(0, 0, At, B0); PG8_MMA(0, 1, At, B1); PG8_BAR; PG8_SCHED;
;             PG8_LDA(At, 1, 1); PG8_STAGE(PG8_SB(1, 0), b3, voffB); PG8_STAGE(PG8_SB(1, 1), b3 + hstep, voffB); PG8_STAGE(PG8_SA(1, 0), a3, voffA);
;             PG8_WAIT_V(8); PG8_WAIT_L(0); PG8_BAR; PG8_MMA(1, 0, At, B0); PG8_MMA(1, 1, At, B1); PG8_BAR; PG8_SCHED;
;         }
	s_setprio 0
	s_add_i32 s29, 0, 0x18000
	s_add_i32 s30, 0, 0x1c000
	v_add_u32_e32 v142, s29, v177
	v_add_u32_e32 v168, s30, v177
	ds_read_b128 v[130:133], v142
	ds_read_b128 v[134:137], v142 offset:1024
	ds_read_b128 v[138:141], v142 offset:2048
	ds_read_b128 v[142:145], v142 offset:3072
	ds_read_b128 v[146:149], v168
	ds_read_b128 v[150:153], v168 offset:1024
	ds_read_b128 v[164:167], v168 offset:2048
	ds_read_b128 v[168:171], v168 offset:3072
	s_add_u32 s54, s72, 0x40000
	s_addc_u32 s55, s73, 0
	s_mov_b32 m0, s45
	ds_read_b128 v[172:175], v181 offset:32768
	ds_read_b128 v[182:185], v181 offset:33792
	ds_read_b128 v[186:189], v181 offset:34816
	ds_read_b128 v[190:193], v181 offset:35840
	ds_read_b128 v[204:207], v181 offset:36864
	ds_read_b128 v[208:211], v181 offset:37888
	ds_read_b128 v[212:215], v181 offset:38912
	ds_read_b128 v[216:219], v181 offset:39936
	global_load_lds_dwordx4 v154, s[54:55]
	s_mov_b32 m0, s46
	s_nop 0
	global_load_lds_dwordx4 v156, s[54:55]
	s_waitcnt vmcnt(8)
	s_waitcnt lgkmcnt(0)
	s_barrier
	s_setprio 1
	v_mfma_f32_16x16x32_bf16 v[126:129], v[130:133], v[172:175], v[126:129]
	v_mfma_f32_16x16x32_bf16 v[122:125], v[138:141], v[172:175], v[122:125]
	v_mfma_f32_16x16x32_bf16 v[110:113], v[130:133], v[186:189], v[110:113]
	v_mfma_f32_16x16x32_bf16 v[106:109], v[138:141], v[186:189], v[106:109]
	v_mfma_f32_16x16x32_bf16 v[94:97], v[130:133], v[204:207], v[94:97]
	v_mfma_f32_16x16x32_bf16 v[90:93], v[138:141], v[204:207], v[90:93]
	v_mfma_f32_16x16x32_bf16 v[78:81], v[130:133], v[212:215], v[78:81]
	v_mfma_f32_16x16x32_bf16 v[74:77], v[138:141], v[212:215], v[74:77]
	v_mfma_f32_16x16x32_bf16 v[126:129], v[134:137], v[182:185], v[126:129]
	v_mfma_f32_16x16x32_bf16 v[122:125], v[142:145], v[182:185], v[122:125]
	v_mfma_f32_16x16x32_bf16 v[110:113], v[134:137], v[190:193], v[110:113]
	v_mfma_f32_16x16x32_bf16 v[106:109], v[142:145], v[190:193], v[106:109]
	v_mfma_f32_16x16x32_bf16 v[94:97], v[134:137], v[208:211], v[94:97]
	v_mfma_f32_16x16x32_bf16 v[90:93], v[142:145], v[208:211], v[90:93]
	v_mfma_f32_16x16x32_bf16 v[78:81], v[134:137], v[216:219], v[78:81]
	v_mfma_f32_16x16x32_bf16 v[74:77], v[142:145], v[216:219], v[74:77]
	v_mfma_f32_16x16x32_bf16 v[118:121], v[146:149], v[172:175], v[118:121]
	v_mfma_f32_16x16x32_bf16 v[114:117], v[164:167], v[172:175], v[114:117]
	v_mfma_f32_16x16x32_bf16 v[102:105], v[146:149], v[186:189], v[102:105]
	v_mfma_f32_16x16x32_bf16 v[98:101], v[164:167], v[186:189], v[98:101]
	v_mfma_f32_16x16x32_bf16 v[86:89], v[146:149], v[204:207], v[86:89]
	v_mfma_f32_16x16x32_bf16 v[82:85], v[164:167], v[204:207], v[82:85]
	v_mfma_f32_16x16x32_bf16 v[70:73], v[146:149], v[212:215], v[70:73]
	v_mfma_f32_16x16x32_bf16 v[66:69], v[164:167], v[212:215], v[66:69]
	v_mfma_f32_16x16x32_bf16 v[118:121], v[150:153], v[182:185], v[118:121]
	v_mfma_f32_16x16x32_bf16 v[114:117], v[168:171], v[182:185], v[114:117]
	v_mfma_f32_16x16x32_bf16 v[102:105], v[150:153], v[190:193], v[102:105]
	v_mfma_f32_16x16x32_bf16 v[98:101], v[168:171], v[190:193], v[98:101]
	v_mfma_f32_16x16x32_bf16 v[86:89], v[150:153], v[208:211], v[86:89]
	v_mfma_f32_16x16x32_bf16 v[82:85], v[168:171], v[208:211], v[82:85]
	v_mfma_f32_16x16x32_bf16 v[70:73], v[150:153], v[216:219], v[70:73]
	v_mfma_f32_16x16x32_bf16 v[66:69], v[168:171], v[216:219], v[66:69]
	s_barrier
	s_setprio 0
	s_add_i32 s29, s29, s15
	s_mov_b32 m0, s29
	ds_read_b128 v[172:175], v181 offset:49152
	ds_read_b128 v[182:185], v181 offset:50176
	ds_read_b128 v[186:189], v181 offset:51200
	ds_read_b128 v[190:193], v181 offset:52224
	ds_read_b128 v[204:207], v181 offset:53248
	ds_read_b128 v[208:211], v181 offset:54272
	ds_read_b128 v[212:215], v181 offset:55296
	ds_read_b128 v[216:219], v181 offset:56320
	global_load_lds_dwordx4 v195, s[20:21]
	s_add_i32 m0, s29, 0x2000
	s_add_i32 s29, s30, s15
	global_load_lds_dwordx4 v201, s[20:21]
	s_add_u32 s20, s20, 0x40080
	s_addc_u32 s21, s21, 0
	s_mov_b32 m0, s29
	s_nop 0
	global_load_lds_dwordx4 v0, s[20:21]
	s_add_i32 m0, s29, 0x2000
	s_nop 0
	global_load_lds_dwordx4 v158, s[20:21]
	s_mov_b32 m0, s12
	s_nop 0
	global_load_lds_dwordx4 v221, s[72:73]
	s_mov_b32 m0, s47
	s_nop 0
	global_load_lds_dwordx4 v223, s[72:73]
	s_waitcnt vmcnt(8)
	s_waitcnt lgkmcnt(0)
	s_barrier
	s_setprio 1
	v_mfma_f32_16x16x32_bf16 v[62:65], v[130:133], v[172:175], v[62:65]
	v_mfma_f32_16x16x32_bf16 v[58:61], v[138:141], v[172:175], v[58:61]
	v_mfma_f32_16x16x32_bf16 v[46:49], v[130:133], v[186:189], v[46:49]
	v_mfma_f32_16x16x32_bf16 v[42:45], v[138:141], v[186:189], v[42:45]
	v_mfma_f32_16x16x32_bf16 v[30:33], v[130:133], v[204:207], v[30:33]
	v_mfma_f32_16x16x32_bf16 v[26:29], v[138:141], v[204:207], v[26:29]
	v_mfma_f32_16x16x32_bf16 v[14:17], v[130:133], v[212:215], v[14:17]
	v_mfma_f32_16x16x32_bf16 v[10:13], v[138:141], v[212:215], v[10:13]
	v_mfma_f32_16x16x32_bf16 v[62:65], v[134:137], v[182:185], v[62:65]
	v_mfma_f32_16x16x32_bf16 v[58:61], v[142:145], v[182:185], v[58:61]
	v_mfma_f32_16x16x32_bf16 v[46:49], v[134:137], v[190:193], v[46:49]
	v_mfma_f32_16x16x32_bf16 v[42:45], v[142:145], v[190:193], v[42:45]
	v_mfma_f32_16x16x32_bf16 v[30:33], v[134:137], v[208:211], v[30:33]
	v_mfma_f32_16x16x32_bf16 v[26:29], v[142:145], v[208:211], v[26:29]
	v_mfma_f32_16x16x32_bf16 v[14:17], v[134:137], v[216:219], v[14:17]
	v_mfma_f32_16x16x32_bf16 v[10:13], v[142:145], v[216:219], v[10:13]
	v_mfma_f32_16x16x32_bf16 v[54:57], v[146:149], v[172:175], v[54:57]
	v_mfma_f32_16x16x32_bf16 v[50:53], v[164:167], v[172:175], v[50:53]
	v_mfma_f32_16x16x32_bf16 v[38:41], v[146:149], v[186:189], v[38:41]
	v_mfma_f32_16x16x32_bf16 v[34:37], v[164:167], v[186:189], v[34:37]
	v_mfma_f32_16x16x32_bf16 v[22:25], v[146:149], v[204:207], v[22:25]
	v_mfma_f32_16x16x32_bf16 v[18:21], v[164:167], v[204:207], v[18:21]
	v_mfma_f32_16x16x32_bf16 v[6:9], v[146:149], v[212:215], v[6:9]
	v_mfma_f32_16x16x32_bf16 v[2:5], v[164:167], v[212:215], v[2:5]
	v_mfma_f32_16x16x32_bf16 v[54:57], v[150:153], v[182:185], v[54:57]
	v_mfma_f32_16x16x32_bf16 v[50:53], v[168:171], v[182:185], v[50:53]
	v_mfma_f32_16x16x32_bf16 v[38:41], v[150:153], v[190:193], v[38:41]
	v_mfma_f32_16x16x32_bf16 v[34:37], v[168:171], v[190:193], v[34:37]
	v_mfma_f32_16x16x32_bf16 v[22:25], v[150:153], v[208:211], v[22:25]
	v_mfma_f32_16x16x32_bf16 v[18:21], v[168:171], v[208:211], v[18:21]
	v_mfma_f32_16x16x32_bf16 v[6:9], v[150:153], v[216:219], v[6:9]
	v_mfma_f32_16x16x32_bf16 v[2:5], v[168:171], v[216:219], v[2:5]
	s_barrier
	s_setprio 0
	s_add_i32 s53, s53, 2
	s_add_u32 s51, s51, 0x100
	s_addc_u32 s52, s52, 0
	s_add_u32 s92, s92, 0x100
	s_addc_u32 s93, s93, 0
	s_cmp_gt_u32 s53, 13
	s_cbranch_scc0 .LBB0_397
	s_and_b64 vcc, exec, s[10:11]
	s_cbranch_vccz .LBB0_400
	s_barrier

;     __device__ bool next(int i, Unit& u) const { if (!b.next(i / 3, u)) return false; u.pz = i % 3; return true; }
; #define PG8_STAGE(bufoff, gbase, voff) do { _Pragma("unroll") for (int _i = 0; _i < 2; ++_i) \
;         __builtin_amdgcn_global_load_lds((const gunsigned*)((const gchar*)(gbase) + (voff)[_i]), (LAS unsigned*)(lds + (bufoff) + ldsw + _i * 8192), 16, 0, 0); } while (0)
; #define PG8_LDA(dst, b, h) do { _Pragma("unroll") for (int m = 0; m < 4; ++m) _Pragma("unroll") for (int k = 0; k < 2; ++k) dst[m][k] = *(const LAS bf16x8*)(lds + PG8_SA(b, h) + aoff + m * 2048 + k * 1024); } while (0)
; #define PG8_LDB(dst, b, h) do { _Pragma("unroll") for (int n = 0; n < 2; ++n) _Pragma("unroll") for (int k = 0; k < 2; ++k) dst[n][k] = *(const LAS bf16x8*)(lds + PG8_SB(b, h) + boff + n * 2048 + k * 1024); } while (0)
; #define PG8_WAIT_V(n) asm volatile("s_waitcnt vmcnt(" #n ")" ::: "memory")
; #define PG8_WAIT_L(n) asm volatile("s_waitcnt lgkmcnt(" #n ")" ::: "memory")
; #define PG8_BAR __builtin_amdgcn_s_barrier()
; template <class Epi, class Sched>
; __device__ __forceinline__ void gemm_phase(LAS unsigned char* lds, const int tid, const Gemm g, const Sched& S, const Epi& E) {
;     ...
;         const bool has_next = S.next(ui + 1, nxt);
;         const gchar* nA = has_next ? (const gchar*)g.A + (size_t)nxt.pm * tstep + (size_t)nxt.pz * g.zA : cA;
;         const gchar* nB = has_next ? (const gchar*)g.Bt + (size_t)nxt.pn * tstep + (size_t)nxt.pz * g.zB : cB;
;         for (int t = 0; t < nt; t += 2) {
;             const bool last = (t == nt - 2);
;             const gchar* a1 = cA + (size_t)(t + 1) * kstep;
;             const gchar* a2 = last ? nA : cA + (size_t)(t + 2) * kstep; const gchar* b2 = last ? nB : cB + (size_t)(t + 2) * kstep;
;             const gchar* a3 = a2 + kstep; const gchar* b3 = b2 + kstep;
;             PG8_LDB(B0, 0, 0); PG8_LDB(B1, 0, 1); PG8_SCHED; PG8_LDA(At, 0, 0); PG8_STAGE(PG8_SA(1, 1), a1 + hstep, voffA);
;             PG8_WAIT_V(8); PG8_WAIT_L(0); PG8_BAR; PG8_MMA(0, 0, At, B0); PG8_MMA(0, 1, At, B1); PG8_BAR; PG8_SCHED;
;             PG8_LDA(At, 0, 1); PG8_STAGE(PG8_SB(0, 0), b2, voffB); PG8_STAGE(PG8_SB(0, 1), b2 + hstep, voffB); PG8_STAGE(PG8_SA(0, 0), a2, voffA);
;             PG8_WAIT_V(8); PG8_WAIT_L(0); PG8_BAR; PG8_MMA(1, 0, At, B0); PG8_MMA(1, 1, At, B1); PG8_BAR; PG8_SCHED;
.LBB0_444:
	s_add_u32 s20, s16, 0xfffe0080
	s_addc_u32 s21, s17, -1
	s_add_i32 s29, 0, 0x10000
	s_cmp_eq_u32 s51, 4
	s_cselect_b32 s73, s1, s21
	s_cselect_b32 s72, s5, s20
	v_add_u32_e32 v122, s29, v242
	s_cselect_b32 s21, s15, s31
	s_cselect_b32 s20, s23, s24
	s_add_i32 s30, 0, 0x14000
	ds_read_b128 v[132:135], v122
	ds_read_b128 v[136:139], v122 offset:1024
	ds_read_b128 v[140:143], v122 offset:2048
	ds_read_b128 v[144:147], v122 offset:3072
	v_add_u32_e32 v122, s30, v242
	ds_read_b128 v[148:151], v122
	ds_read_b128 v[152:155], v122 offset:1024
	ds_read_b128 v[156:159], v122 offset:2048
	ds_read_b128 v[160:163], v122 offset:3072
	s_add_i32 m0, s93, 0xc000
	ds_read_b128 v[164:167], v244
	ds_read_b128 v[168:171], v244 offset:1024
	ds_read_b128 v[172:175], v244 offset:2048
	ds_read_b128 v[176:179], v244 offset:3072
	ds_read_b128 v[180:183], v244 offset:4096
	ds_read_b128 v[184:187], v244 offset:5120
	ds_read_b128 v[188:191], v244 offset:6144
	ds_read_b128 v[192:195], v244 offset:7168
	global_load_lds_dwordx4 v212, s[16:17]
	s_add_i32 m0, s93, 0xe000
	s_nop 0
	global_load_lds_dwordx4 v210, s[16:17]
	s_waitcnt vmcnt(8)
	s_waitcnt lgkmcnt(0)
	s_barrier
	s_setprio 1
	v_mfma_f32_16x16x32_bf16 v[128:131], v[132:135], v[164:167], v[128:131]
	v_mfma_f32_16x16x32_bf16 v[122:125], v[140:143], v[164:167], v[124:127]
	v_mfma_f32_16x16x32_bf16 v[110:113], v[132:135], v[172:175], v[110:113]
	v_mfma_f32_16x16x32_bf16 v[106:109], v[140:143], v[172:175], v[106:109]
	v_mfma_f32_16x16x32_bf16 v[94:97], v[132:135], v[180:183], v[94:97]
	v_mfma_f32_16x16x32_bf16 v[90:93], v[140:143], v[180:183], v[90:93]
	v_mfma_f32_16x16x32_bf16 v[78:81], v[132:135], v[188:191], v[78:81]
	v_mfma_f32_16x16x32_bf16 v[74:77], v[140:143], v[188:191], v[74:77]
	v_mfma_f32_16x16x32_bf16 v[128:131], v[136:139], v[168:171], v[128:131]
	v_mfma_f32_16x16x32_bf16 v[122:125], v[144:147], v[168:171], v[122:125]
	v_mfma_f32_16x16x32_bf16 v[110:113], v[136:139], v[176:179], v[110:113]
	v_mfma_f32_16x16x32_bf16 v[106:109], v[144:147], v[176:179], v[106:109]
	v_mfma_f32_16x16x32_bf16 v[94:97], v[136:139], v[184:187], v[94:97]
	v_mfma_f32_16x16x32_bf16 v[90:93], v[144:147], v[184:187], v[90:93]
	v_mfma_f32_16x16x32_bf16 v[78:81], v[136:139], v[192:195], v[78:81]
	v_mfma_f32_16x16x32_bf16 v[74:77], v[144:147], v[192:195], v[74:77]
	v_mfma_f32_16x16x32_bf16 v[118:121], v[148:151], v[164:167], v[118:121]
	v_mfma_f32_16x16x32_bf16 v[114:117], v[156:159], v[164:167], v[114:117]
	v_mfma_f32_16x16x32_bf16 v[102:105], v[148:151], v[172:175], v[102:105]
	v_mfma_f32_16x16x32_bf16 v[98:101], v[156:159], v[172:175], v[98:101]
	v_mfma_f32_16x16x32_bf16 v[86:89], v[148:151], v[180:183], v[86:89]
	v_mfma_f32_16x16x32_bf16 v[82:85], v[156:159], v[180:183], v[82:85]
	v_mfma_f32_16x16x32_bf16 v[70:73], v[148:151], v[188:191], v[70:73]
	v_mfma_f32_16x16x32_bf16 v[66:69], v[156:159], v[188:191], v[66:69]
	v_mfma_f32_16x16x32_bf16 v[118:121], v[152:155], v[168:171], v[118:121]
	v_mfma_f32_16x16x32_bf16 v[114:117], v[160:163], v[168:171], v[114:117]
	v_mfma_f32_16x16x32_bf16 v[102:105], v[152:155], v[176:179], v[102:105]
	v_mfma_f32_16x16x32_bf16 v[98:101], v[160:163], v[176:179], v[98:101]
	v_mfma_f32_16x16x32_bf16 v[86:89], v[152:155], v[184:187], v[86:89]
	v_mfma_f32_16x16x32_bf16 v[82:85], v[160:163], v[184:187], v[82:85]
	v_mfma_f32_16x16x32_bf16 v[70:73], v[152:155], v[192:195], v[70:73]
	v_mfma_f32_16x16x32_bf16 v[66:69], v[160:163], v[192:195], v[66:69]
	s_barrier
	s_setprio 0
	s_add_i32 s29, s29, s42
	s_mov_b32 m0, s29
	ds_read_b128 v[164:167], v244 offset:16384
	ds_read_b128 v[168:171], v244 offset:17408
	ds_read_b128 v[172:175], v244 offset:18432
	ds_read_b128 v[176:179], v244 offset:19456
	ds_read_b128 v[180:183], v244 offset:20480
	ds_read_b128 v[184:187], v244 offset:21504
	ds_read_b128 v[188:191], v244 offset:22528
	ds_read_b128 v[192:195], v244 offset:23552
	global_load_lds_dwordx4 v0, s[20:21]
	s_add_i32 m0, s29, 0x2000
	s_add_u32 s52, s20, 0x20000
	s_addc_u32 s53, s21, 0
	s_add_i32 s29, s30, s42
	global_load_lds_dwordx4 v208, s[20:21]
	s_mov_b32 m0, s29
	s_nop 0
	global_load_lds_dwordx4 v0, s[52:53]
	s_add_i32 m0, s29, 0x2000
	s_nop 0
	global_load_lds_dwordx4 v208, s[52:53]
	s_mov_b32 m0, s93
	s_nop 0
	global_load_lds_dwordx4 v204, s[72:73]
	s_mov_b32 m0, s44
	s_nop 0
	global_load_lds_dwordx4 v206, s[72:73]
	s_waitcnt vmcnt(8)
	s_waitcnt lgkmcnt(0)
	s_barrier
	s_setprio 1
	v_mfma_f32_16x16x32_bf16 v[62:65], v[132:135], v[164:167], v[62:65]
	v_mfma_f32_16x16x32_bf16 v[58:61], v[140:143], v[164:167], v[58:61]
	v_mfma_f32_16x16x32_bf16 v[46:49], v[132:135], v[172:175], v[46:49]
	v_mfma_f32_16x16x32_bf16 v[42:45], v[140:143], v[172:175], v[42:45]
	v_mfma_f32_16x16x32_bf16 v[30:33], v[132:135], v[180:183], v[30:33]
	v_mfma_f32_16x16x32_bf16 v[26:29], v[140:143], v[180:183], v[26:29]
	v_mfma_f32_16x16x32_bf16 v[14:17], v[132:135], v[188:191], v[14:17]
	v_mfma_f32_16x16x32_bf16 v[10:13], v[140:143], v[188:191], v[10:13]
	v_mfma_f32_16x16x32_bf16 v[62:65], v[136:139], v[168:171], v[62:65]
	v_mfma_f32_16x16x32_bf16 v[58:61], v[144:147], v[168:171], v[58:61]
	v_mfma_f32_16x16x32_bf16 v[46:49], v[136:139], v[176:179], v[46:49]
	v_mfma_f32_16x16x32_bf16 v[42:45], v[144:147], v[176:179], v[42:45]
	v_mfma_f32_16x16x32_bf16 v[30:33], v[136:139], v[184:187], v[30:33]
	v_mfma_f32_16x16x32_bf16 v[26:29], v[144:147], v[184:187], v[26:29]
	v_mfma_f32_16x16x32_bf16 v[14:17], v[136:139], v[192:195], v[14:17]
	v_mfma_f32_16x16x32_bf16 v[10:13], v[144:147], v[192:195], v[10:13]
	v_mfma_f32_16x16x32_bf16 v[54:57], v[148:151], v[164:167], v[54:57]
	v_mfma_f32_16x16x32_bf16 v[50:53], v[156:159], v[164:167], v[50:53]
	v_mfma_f32_16x16x32_bf16 v[38:41], v[148:151], v[172:175], v[38:41]
	v_mfma_f32_16x16x32_bf16 v[34:37], v[156:159], v[172:175], v[34:37]
	v_mfma_f32_16x16x32_bf16 v[22:25], v[148:151], v[180:183], v[22:25]
	v_mfma_f32_16x16x32_bf16 v[18:21], v[156:159], v[180:183], v[18:21]
	v_mfma_f32_16x16x32_bf16 v[6:9], v[148:151], v[188:191], v[6:9]
	v_mfma_f32_16x16x32_bf16 v[2:5], v[156:159], v[188:191], v[2:5]
	v_mfma_f32_16x16x32_bf16 v[54:57], v[152:155], v[168:171], v[54:57]
	v_mfma_f32_16x16x32_bf16 v[50:53], v[160:163], v[168:171], v[50:53]
	v_mfma_f32_16x16x32_bf16 v[38:41], v[152:155], v[176:179], v[38:41]
	v_mfma_f32_16x16x32_bf16 v[34:37], v[160:163], v[176:179], v[34:37]
	v_mfma_f32_16x16x32_bf16 v[22:25], v[152:155], v[184:187], v[22:25]
	v_mfma_f32_16x16x32_bf16 v[18:21], v[160:163], v[184:187], v[18:21]
	v_mfma_f32_16x16x32_bf16 v[6:9], v[152:155], v[192:195], v[6:9]
	v_mfma_f32_16x16x32_bf16 v[2:5], v[160:163], v[192:195], v[2:5]
	s_barrier
; #define PG8_STAGE(bufoff, gbase, voff) do { _Pragma("unroll") for (int _i = 0; _i < 2; ++_i) \
;         __builtin_amdgcn_global_load_lds((const gunsigned*)((const gchar*)(gbase) + (voff)[_i]), (LAS unsigned*)(lds + (bufoff) + ldsw + _i * 8192), 16, 0, 0); } while (0)
; #define PG8_LDA(dst, b, h) do { _Pragma("unroll") for (int m = 0; m < 4; ++m) _Pragma("unroll") for (int k = 0; k < 2; ++k) dst[m][k] = *(const LAS bf16x8*)(lds + PG8_SA(b, h) + aoff + m * 2048 + k * 1024); } while (0)
; #define PG8_LDB(dst, b, h) do { _Pragma("unroll") for (int n = 0; n < 2; ++n) _Pragma("unroll") for (int k = 0; k < 2; ++k) dst[n][k] = *(const LAS bf16x8*)(lds + PG8_SB(b, h) + boff + n * 2048 + k * 1024); } while (0)
; #define PG8_MMA(ai, bj, At, Bt) do { __builtin_amdgcn_s_setprio(1); _Pragma("unroll") for (int m = 0; m < 4; ++m) _Pragma("unroll") for (int n = 0; n < 2; ++n) _Pragma("unroll") for (int k = 0; k < 2; ++k) \
;         acc[ai][bj][m][n] = __builtin_amdgcn_mfma_f32_16x16x32_bf16(Bt[n][k], At[m][k], acc[ai][bj][m][n], 0, 0, 0); __builtin_amdgcn_s_setprio(0); } while (0)
; #define PG8_WAIT_V(n) asm volatile("s_waitcnt vmcnt(" #n ")" ::: "memory")
; #define PG8_WAIT_L(n) asm volatile("s_waitcnt lgkmcnt(" #n ")" ::: "memory")
; #define PG8_BAR __builtin_amdgcn_s_barrier()
; #define PG8_SCHED __builtin_amdgcn_sched_barrier(0)
; template <class Epi, class Sched>
; __device__ __forceinline__ void gemm_phase(LAS unsigned char* lds, const int tid, const Gemm g, const Sched& S, const Epi& E) {
;     ...
;             PG8_LDB(B0, 1, 0); PG8_LDB(B1, 1, 1); PG8_SCHED; PG8_LDA(At, 1, 0); PG8_STAGE(PG8_SA(0, 1), a2 + hstep, voffA);
;             PG8_WAIT_V(8); PG8_WAIT_L(0); PG8_BAR; PG8_MMA(0, 0, At, B0); PG8_MMA(0, 1, At, B1); PG8_BAR; PG8_SCHED;
;             PG8_LDA(At, 1, 1); PG8_STAGE(PG8_SB(1, 0), b3, voffB); PG8_STAGE(PG8_SB(1, 1), b3 + hstep, voffB); PG8_STAGE(PG8_SA(1, 0), a3, voffA);
;             PG8_WAIT_V(8); PG8_WAIT_L(0); PG8_BAR; PG8_MMA(1, 0, At, B0); PG8_MMA(1, 1, At, B1); PG8_BAR; PG8_SCHED;
;         }
	s_setprio 0
	s_add_i32 s29, 0, 0x18000
	v_add_u32_e32 v126, s29, v242
	s_add_i32 s30, 0, 0x1c000
	ds_read_b128 v[132:135], v126
	ds_read_b128 v[136:139], v126 offset:1024
	ds_read_b128 v[140:143], v126 offset:2048
	ds_read_b128 v[144:147], v126 offset:3072
	v_add_u32_e32 v126, s30, v242
	ds_read_b128 v[148:151], v126
	ds_read_b128 v[152:155], v126 offset:1024
	ds_read_b128 v[156:159], v126 offset:2048
	ds_read_b128 v[160:163], v126 offset:3072
	s_add_u32 s52, s72, 0x20000
	s_addc_u32 s53, s73, 0
	s_mov_b32 m0, s45
	ds_read_b128 v[164:167], v244 offset:32768
	ds_read_b128 v[168:171], v244 offset:33792
	ds_read_b128 v[172:175], v244 offset:34816
	ds_read_b128 v[176:179], v244 offset:35840
	ds_read_b128 v[180:183], v244 offset:36864
	ds_read_b128 v[184:187], v244 offset:37888
	ds_read_b128 v[188:191], v244 offset:38912
	ds_read_b128 v[192:195], v244 offset:39936
	global_load_lds_dwordx4 v204, s[52:53]
	s_mov_b32 m0, s46
	s_nop 0
	global_load_lds_dwordx4 v206, s[52:53]
	s_waitcnt vmcnt(8)
	s_waitcnt lgkmcnt(0)
	s_barrier
	s_setprio 1
	v_mfma_f32_16x16x32_bf16 v[126:129], v[132:135], v[164:167], v[128:131]
	v_mfma_f32_16x16x32_bf16 v[122:125], v[140:143], v[164:167], v[122:125]
	v_mfma_f32_16x16x32_bf16 v[110:113], v[132:135], v[172:175], v[110:113]
	v_mfma_f32_16x16x32_bf16 v[106:109], v[140:143], v[172:175], v[106:109]
	v_mfma_f32_16x16x32_bf16 v[94:97], v[132:135], v[180:183], v[94:97]
	v_mfma_f32_16x16x32_bf16 v[90:93], v[140:143], v[180:183], v[90:93]
	v_mfma_f32_16x16x32_bf16 v[78:81], v[132:135], v[188:191], v[78:81]
	v_mfma_f32_16x16x32_bf16 v[74:77], v[140:143], v[188:191], v[74:77]
	v_mfma_f32_16x16x32_bf16 v[128:131], v[136:139], v[168:171], v[126:129]
	v_mfma_f32_16x16x32_bf16 v[124:127], v[144:147], v[168:171], v[122:125]
	v_mfma_f32_16x16x32_bf16 v[110:113], v[136:139], v[176:179], v[110:113]
	v_mfma_f32_16x16x32_bf16 v[106:109], v[144:147], v[176:179], v[106:109]
	v_mfma_f32_16x16x32_bf16 v[94:97], v[136:139], v[184:187], v[94:97]
	v_mfma_f32_16x16x32_bf16 v[90:93], v[144:147], v[184:187], v[90:93]
	v_mfma_f32_16x16x32_bf16 v[78:81], v[136:139], v[192:195], v[78:81]
	v_mfma_f32_16x16x32_bf16 v[74:77], v[144:147], v[192:195], v[74:77]
	v_mfma_f32_16x16x32_bf16 v[118:121], v[148:151], v[164:167], v[118:121]
	v_mfma_f32_16x16x32_bf16 v[114:117], v[156:159], v[164:167], v[114:117]
	v_mfma_f32_16x16x32_bf16 v[102:105], v[148:151], v[172:175], v[102:105]
	v_mfma_f32_16x16x32_bf16 v[98:101], v[156:159], v[172:175], v[98:101]
	v_mfma_f32_16x16x32_bf16 v[86:89], v[148:151], v[180:183], v[86:89]
	v_mfma_f32_16x16x32_bf16 v[82:85], v[156:159], v[180:183], v[82:85]
	v_mfma_f32_16x16x32_bf16 v[70:73], v[148:151], v[188:191], v[70:73]
	v_mfma_f32_16x16x32_bf16 v[66:69], v[156:159], v[188:191], v[66:69]
	v_mfma_f32_16x16x32_bf16 v[118:121], v[152:155], v[168:171], v[118:121]
	v_mfma_f32_16x16x32_bf16 v[114:117], v[160:163], v[168:171], v[114:117]
	v_mfma_f32_16x16x32_bf16 v[102:105], v[152:155], v[176:179], v[102:105]
	v_mfma_f32_16x16x32_bf16 v[98:101], v[160:163], v[176:179], v[98:101]
	v_mfma_f32_16x16x32_bf16 v[86:89], v[152:155], v[184:187], v[86:89]
	v_mfma_f32_16x16x32_bf16 v[82:85], v[160:163], v[184:187], v[82:85]
	v_mfma_f32_16x16x32_bf16 v[70:73], v[152:155], v[192:195], v[70:73]
	v_mfma_f32_16x16x32_bf16 v[66:69], v[160:163], v[192:195], v[66:69]
	s_barrier
	s_setprio 0
	s_add_i32 s29, s29, s42
	s_mov_b32 m0, s29
	ds_read_b128 v[164:167], v244 offset:49152
	ds_read_b128 v[168:171], v244 offset:50176
	ds_read_b128 v[172:175], v244 offset:51200
	ds_read_b128 v[176:179], v244 offset:52224
	ds_read_b128 v[180:183], v244 offset:53248
	ds_read_b128 v[184:187], v244 offset:54272
	ds_read_b128 v[188:191], v244 offset:55296
	ds_read_b128 v[192:195], v244 offset:56320
	global_load_lds_dwordx4 v201, s[20:21]
	s_add_i32 m0, s29, 0x2000
	s_add_i32 s29, s30, s42
	global_load_lds_dwordx4 v215, s[20:21]
	s_add_u32 s20, s20, 0x20080
	s_addc_u32 s21, s21, 0
	s_mov_b32 m0, s29
	s_nop 0
	global_load_lds_dwordx4 v0, s[20:21]
	s_add_i32 m0, s29, 0x2000
	s_nop 0
	global_load_lds_dwordx4 v208, s[20:21]
	s_mov_b32 m0, s47
	s_nop 0
	global_load_lds_dwordx4 v217, s[72:73]
	s_mov_b32 m0, s48
	s_nop 0
	global_load_lds_dwordx4 v219, s[72:73]
	s_waitcnt vmcnt(8)
	s_waitcnt lgkmcnt(0)
	s_barrier
	s_setprio 1
	v_mfma_f32_16x16x32_bf16 v[62:65], v[132:135], v[164:167], v[62:65]
	v_mfma_f32_16x16x32_bf16 v[58:61], v[140:143], v[164:167], v[58:61]
	v_mfma_f32_16x16x32_bf16 v[46:49], v[132:135], v[172:175], v[46:49]
	v_mfma_f32_16x16x32_bf16 v[42:45], v[140:143], v[172:175], v[42:45]
	v_mfma_f32_16x16x32_bf16 v[30:33], v[132:135], v[180:183], v[30:33]
	v_mfma_f32_16x16x32_bf16 v[26:29], v[140:143], v[180:183], v[26:29]
	v_mfma_f32_16x16x32_bf16 v[14:17], v[132:135], v[188:191], v[14:17]
	v_mfma_f32_16x16x32_bf16 v[10:13], v[140:143], v[188:191], v[10:13]
	v_mfma_f32_16x16x32_bf16 v[62:65], v[136:139], v[168:171], v[62:65]
	v_mfma_f32_16x16x32_bf16 v[58:61], v[144:147], v[168:171], v[58:61]
	v_mfma_f32_16x16x32_bf16 v[46:49], v[136:139], v[176:179], v[46:49]
	v_mfma_f32_16x16x32_bf16 v[42:45], v[144:147], v[176:179], v[42:45]
	v_mfma_f32_16x16x32_bf16 v[30:33], v[136:139], v[184:187], v[30:33]
	v_mfma_f32_16x16x32_bf16 v[26:29], v[144:147], v[184:187], v[26:29]
	v_mfma_f32_16x16x32_bf16 v[14:17], v[136:139], v[192:195], v[14:17]
	v_mfma_f32_16x16x32_bf16 v[10:13], v[144:147], v[192:195], v[10:13]
	v_mfma_f32_16x16x32_bf16 v[54:57], v[148:151], v[164:167], v[54:57]
	v_mfma_f32_16x16x32_bf16 v[50:53], v[156:159], v[164:167], v[50:53]
	v_mfma_f32_16x16x32_bf16 v[38:41], v[148:151], v[172:175], v[38:41]
	v_mfma_f32_16x16x32_bf16 v[34:37], v[156:159], v[172:175], v[34:37]
	v_mfma_f32_16x16x32_bf16 v[22:25], v[148:151], v[180:183], v[22:25]
	v_mfma_f32_16x16x32_bf16 v[18:21], v[156:159], v[180:183], v[18:21]
	v_mfma_f32_16x16x32_bf16 v[6:9], v[148:151], v[188:191], v[6:9]
	v_mfma_f32_16x16x32_bf16 v[2:5], v[156:159], v[188:191], v[2:5]
	v_mfma_f32_16x16x32_bf16 v[54:57], v[152:155], v[168:171], v[54:57]
	v_mfma_f32_16x16x32_bf16 v[50:53], v[160:163], v[168:171], v[50:53]
	v_mfma_f32_16x16x32_bf16 v[38:41], v[152:155], v[176:179], v[38:41]
	v_mfma_f32_16x16x32_bf16 v[34:37], v[160:163], v[176:179], v[34:37]
	v_mfma_f32_16x16x32_bf16 v[22:25], v[152:155], v[184:187], v[22:25]
	v_mfma_f32_16x16x32_bf16 v[18:21], v[160:163], v[184:187], v[18:21]
	v_mfma_f32_16x16x32_bf16 v[6:9], v[152:155], v[192:195], v[6:9]
	v_mfma_f32_16x16x32_bf16 v[2:5], v[160:163], v[192:195], v[2:5]
	s_barrier
	s_setprio 0
	s_add_i32 s51, s51, 2
	s_add_u32 s24, s24, 0x100
	s_addc_u32 s31, s31, 0
	s_add_u32 s16, s16, 0x100
	s_addc_u32 s17, s17, 0
	s_cmp_gt_u32 s51, 5
	s_cbranch_scc0 .LBB0_444
	s_and_b64 vcc, exec, s[10:11]
	s_cbranch_vccz .LBB0_447
	s_barrier

;     __device__ bool next(int i, Unit& u) const { if (!b.next(i / 3, u)) return false; u.pz = i % 3; return true; }
; #define PG8_STAGE(bufoff, gbase, voff) do { _Pragma("unroll") for (int _i = 0; _i < 2; ++_i) \
;         __builtin_amdgcn_global_load_lds((const gunsigned*)((const gchar*)(gbase) + (voff)[_i]), (LAS unsigned*)(lds + (bufoff) + ldsw + _i * 8192), 16, 0, 0); } while (0)
; #define PG8_LDA(dst, b, h) do { _Pragma("unroll") for (int m = 0; m < 4; ++m) _Pragma("unroll") for (int k = 0; k < 2; ++k) dst[m][k] = *(const LAS bf16x8*)(lds + PG8_SA(b, h) + aoff + m * 2048 + k * 1024); } while (0)
; #define PG8_LDB(dst, b, h) do { _Pragma("unroll") for (int n = 0; n < 2; ++n) _Pragma("unroll") for (int k = 0; k < 2; ++k) dst[n][k] = *(const LAS bf16x8*)(lds + PG8_SB(b, h) + boff + n * 2048 + k * 1024); } while (0)
; #define PG8_WAIT_V(n) asm volatile("s_waitcnt vmcnt(" #n ")" ::: "memory")
; #define PG8_WAIT_L(n) asm volatile("s_waitcnt lgkmcnt(" #n ")" ::: "memory")
; #define PG8_BAR __builtin_amdgcn_s_barrier()
; template <class Epi, class Sched>
; __device__ __forceinline__ void gemm_phase(LAS unsigned char* lds, const int tid, const Gemm g, const Sched& S, const Epi& E) {
;     ...
;         const bool has_next = S.next(ui + 1, nxt);
;         const gchar* nA = has_next ? (const gchar*)g.A + (size_t)nxt.pm * tstep + (size_t)nxt.pz * g.zA : cA;
;         const gchar* nB = has_next ? (const gchar*)g.Bt + (size_t)nxt.pn * tstep + (size_t)nxt.pz * g.zB : cB;
;         for (int t = 0; t < nt; t += 2) {
;             const bool last = (t == nt - 2);
;             const gchar* a1 = cA + (size_t)(t + 1) * kstep;
;             const gchar* a2 = last ? nA : cA + (size_t)(t + 2) * kstep; const gchar* b2 = last ? nB : cB + (size_t)(t + 2) * kstep;
;             const gchar* a3 = a2 + kstep; const gchar* b3 = b2 + kstep;
;             PG8_LDB(B0, 0, 0); PG8_LDB(B1, 0, 1); PG8_SCHED; PG8_LDA(At, 0, 0); PG8_STAGE(PG8_SA(1, 1), a1 + hstep, voffA);
;             PG8_WAIT_V(8); PG8_WAIT_L(0); PG8_BAR; PG8_MMA(0, 0, At, B0); PG8_MMA(0, 1, At, B1); PG8_BAR; PG8_SCHED;
;             PG8_LDA(At, 0, 1); PG8_STAGE(PG8_SB(0, 0), b2, voffB); PG8_STAGE(PG8_SB(0, 1), b2 + hstep, voffB); PG8_STAGE(PG8_SA(0, 0), a2, voffA);
;             PG8_WAIT_V(8); PG8_WAIT_L(0); PG8_BAR; PG8_MMA(1, 0, At, B0); PG8_MMA(1, 1, At, B1); PG8_BAR; PG8_SCHED;
.LBB0_559:
	s_add_u32 s20, s60, 0xfffc0080
	s_addc_u32 s21, s61, -1
	s_add_i32 s29, 0, 0x10000
	s_cmp_eq_u32 s46, 12
	s_cselect_b32 s63, s9, s21
	s_cselect_b32 s62, s42, s20
	s_cselect_b32 s21, s7, s45
	s_cselect_b32 s20, s43, s44
	s_add_i32 s30, 0, 0x14000
	v_add_u32_e32 v152, s29, v165
	v_add_u32_e32 v160, s30, v165
	ds_read_b128 v[130:133], v152
	ds_read_b128 v[144:147], v152 offset:1024
	ds_read_b128 v[148:151], v152 offset:2048
	ds_read_b128 v[152:155], v152 offset:3072
	ds_read_b128 v[156:159], v160
	ds_read_b128 v[170:173], v160 offset:1024
	ds_read_b128 v[174:177], v160 offset:2048
	ds_read_b128 v[178:181], v160 offset:3072
	s_add_i32 m0, s34, 0xc000
	ds_read_b128 v[182:185], v169
	ds_read_b128 v[186:189], v169 offset:1024
	ds_read_b128 v[190:193], v169 offset:2048
	ds_read_b128 v[204:207], v169 offset:3072
	ds_read_b128 v[210:213], v169 offset:4096
	ds_read_b128 v[214:217], v169 offset:5120
	ds_read_b128 v[218:221], v169 offset:6144
	ds_read_b128 v[222:225], v169 offset:7168
	global_load_lds_dwordx4 v142, s[60:61]
	s_add_i32 m0, s34, 0xe000
	s_nop 0
	global_load_lds_dwordx4 v140, s[60:61]
	s_waitcnt vmcnt(8)
	s_waitcnt lgkmcnt(0)
	s_barrier
	s_setprio 1
	v_mfma_f32_16x16x32_bf16 v[126:129], v[130:133], v[182:185], v[126:129]
	v_mfma_f32_16x16x32_bf16 v[122:125], v[148:151], v[182:185], v[122:125]
	v_mfma_f32_16x16x32_bf16 v[118:121], v[130:133], v[190:193], v[118:121]
	v_mfma_f32_16x16x32_bf16 v[110:113], v[148:151], v[190:193], v[110:113]
	v_mfma_f32_16x16x32_bf16 v[102:105], v[130:133], v[210:213], v[102:105]
	v_mfma_f32_16x16x32_bf16 v[94:97], v[148:151], v[210:213], v[94:97]
	v_mfma_f32_16x16x32_bf16 v[86:89], v[130:133], v[218:221], v[86:89]
	v_mfma_f32_16x16x32_bf16 v[78:81], v[148:151], v[218:221], v[78:81]
	v_mfma_f32_16x16x32_bf16 v[126:129], v[144:147], v[186:189], v[126:129]
	v_mfma_f32_16x16x32_bf16 v[122:125], v[152:155], v[186:189], v[122:125]
	v_mfma_f32_16x16x32_bf16 v[118:121], v[144:147], v[204:207], v[118:121]
	v_mfma_f32_16x16x32_bf16 v[110:113], v[152:155], v[204:207], v[110:113]
	v_mfma_f32_16x16x32_bf16 v[102:105], v[144:147], v[214:217], v[102:105]
	v_mfma_f32_16x16x32_bf16 v[94:97], v[152:155], v[214:217], v[94:97]
	v_mfma_f32_16x16x32_bf16 v[86:89], v[144:147], v[222:225], v[86:89]
	v_mfma_f32_16x16x32_bf16 v[78:81], v[152:155], v[222:225], v[78:81]
	v_mfma_f32_16x16x32_bf16 v[114:117], v[156:159], v[182:185], v[114:117]
	v_mfma_f32_16x16x32_bf16 v[106:109], v[174:177], v[182:185], v[106:109]
	v_mfma_f32_16x16x32_bf16 v[98:101], v[156:159], v[190:193], v[98:101]
	v_mfma_f32_16x16x32_bf16 v[90:93], v[174:177], v[190:193], v[90:93]
	v_mfma_f32_16x16x32_bf16 v[82:85], v[156:159], v[210:213], v[82:85]
	v_mfma_f32_16x16x32_bf16 v[74:77], v[174:177], v[210:213], v[74:77]
	v_mfma_f32_16x16x32_bf16 v[70:73], v[156:159], v[218:221], v[70:73]
	v_mfma_f32_16x16x32_bf16 v[66:69], v[174:177], v[218:221], v[66:69]
	v_mfma_f32_16x16x32_bf16 v[114:117], v[170:173], v[186:189], v[114:117]
	v_mfma_f32_16x16x32_bf16 v[106:109], v[178:181], v[186:189], v[106:109]
	v_mfma_f32_16x16x32_bf16 v[98:101], v[170:173], v[204:207], v[98:101]
	v_mfma_f32_16x16x32_bf16 v[90:93], v[178:181], v[204:207], v[90:93]
	v_mfma_f32_16x16x32_bf16 v[82:85], v[170:173], v[214:217], v[82:85]
	v_mfma_f32_16x16x32_bf16 v[74:77], v[178:181], v[214:217], v[74:77]
	v_mfma_f32_16x16x32_bf16 v[70:73], v[170:173], v[222:225], v[70:73]
	v_mfma_f32_16x16x32_bf16 v[66:69], v[178:181], v[222:225], v[66:69]
	s_barrier
	s_setprio 0
	s_add_i32 s29, s29, s12
	s_mov_b32 m0, s29
	ds_read_b128 v[182:185], v169 offset:16384
	ds_read_b128 v[186:189], v169 offset:17408
	ds_read_b128 v[190:193], v169 offset:18432
	ds_read_b128 v[204:207], v169 offset:19456
	ds_read_b128 v[210:213], v169 offset:20480
	ds_read_b128 v[214:217], v169 offset:21504
	ds_read_b128 v[218:221], v169 offset:22528
	ds_read_b128 v[222:225], v169 offset:23552
	global_load_lds_dwordx4 v0, s[20:21]
	s_add_i32 m0, s29, 0x2000
	s_add_u32 s48, s20, 0x40000
	s_addc_u32 s49, s21, 0
	s_add_i32 s29, s30, s12
	global_load_lds_dwordx4 v134, s[20:21]
	s_mov_b32 m0, s29
	s_nop 0
	global_load_lds_dwordx4 v0, s[48:49]
	s_add_i32 m0, s29, 0x2000
	s_nop 0
	global_load_lds_dwordx4 v134, s[48:49]
	s_mov_b32 m0, s34
	s_nop 0
	global_load_lds_dwordx4 v138, s[62:63]
	s_mov_b32 m0, s35
	s_nop 0
	global_load_lds_dwordx4 v136, s[62:63]
	s_waitcnt vmcnt(8)
	s_waitcnt lgkmcnt(0)
	s_barrier
	s_setprio 1
	v_mfma_f32_16x16x32_bf16 v[62:65], v[130:133], v[182:185], v[62:65]
	v_mfma_f32_16x16x32_bf16 v[58:61], v[148:151], v[182:185], v[58:61]
	v_mfma_f32_16x16x32_bf16 v[54:57], v[130:133], v[190:193], v[54:57]
	v_mfma_f32_16x16x32_bf16 v[46:49], v[148:151], v[190:193], v[46:49]
	v_mfma_f32_16x16x32_bf16 v[38:41], v[130:133], v[210:213], v[38:41]
	v_mfma_f32_16x16x32_bf16 v[30:33], v[148:151], v[210:213], v[30:33]
	v_mfma_f32_16x16x32_bf16 v[22:25], v[130:133], v[218:221], v[22:25]
	v_mfma_f32_16x16x32_bf16 v[14:17], v[148:151], v[218:221], v[14:17]
	v_mfma_f32_16x16x32_bf16 v[62:65], v[144:147], v[186:189], v[62:65]
	v_mfma_f32_16x16x32_bf16 v[58:61], v[152:155], v[186:189], v[58:61]
	v_mfma_f32_16x16x32_bf16 v[54:57], v[144:147], v[204:207], v[54:57]
	v_mfma_f32_16x16x32_bf16 v[46:49], v[152:155], v[204:207], v[46:49]
	v_mfma_f32_16x16x32_bf16 v[38:41], v[144:147], v[214:217], v[38:41]
	v_mfma_f32_16x16x32_bf16 v[30:33], v[152:155], v[214:217], v[30:33]
	v_mfma_f32_16x16x32_bf16 v[22:25], v[144:147], v[222:225], v[22:25]
	v_mfma_f32_16x16x32_bf16 v[14:17], v[152:155], v[222:225], v[14:17]
	v_mfma_f32_16x16x32_bf16 v[50:53], v[156:159], v[182:185], v[50:53]
	v_mfma_f32_16x16x32_bf16 v[42:45], v[174:177], v[182:185], v[42:45]
	v_mfma_f32_16x16x32_bf16 v[34:37], v[156:159], v[190:193], v[34:37]
	v_mfma_f32_16x16x32_bf16 v[26:29], v[174:177], v[190:193], v[26:29]
	v_mfma_f32_16x16x32_bf16 v[18:21], v[156:159], v[210:213], v[18:21]
	v_mfma_f32_16x16x32_bf16 v[10:13], v[174:177], v[210:213], v[10:13]
	v_mfma_f32_16x16x32_bf16 v[6:9], v[156:159], v[218:221], v[6:9]
	v_mfma_f32_16x16x32_bf16 v[2:5], v[174:177], v[218:221], v[2:5]
	v_mfma_f32_16x16x32_bf16 v[50:53], v[170:173], v[186:189], v[50:53]
	v_mfma_f32_16x16x32_bf16 v[42:45], v[178:181], v[186:189], v[42:45]
	v_mfma_f32_16x16x32_bf16 v[34:37], v[170:173], v[204:207], v[34:37]
	v_mfma_f32_16x16x32_bf16 v[26:29], v[178:181], v[204:207], v[26:29]
	v_mfma_f32_16x16x32_bf16 v[18:21], v[170:173], v[214:217], v[18:21]
	v_mfma_f32_16x16x32_bf16 v[10:13], v[178:181], v[214:217], v[10:13]
	v_mfma_f32_16x16x32_bf16 v[6:9], v[170:173], v[222:225], v[6:9]
	v_mfma_f32_16x16x32_bf16 v[2:5], v[178:181], v[222:225], v[2:5]
	s_barrier
; #define PG8_STAGE(bufoff, gbase, voff) do { _Pragma("unroll") for (int _i = 0; _i < 2; ++_i) \
;         __builtin_amdgcn_global_load_lds((const gunsigned*)((const gchar*)(gbase) + (voff)[_i]), (LAS unsigned*)(lds + (bufoff) + ldsw + _i * 8192), 16, 0, 0); } while (0)
; #define PG8_LDA(dst, b, h) do { _Pragma("unroll") for (int m = 0; m < 4; ++m) _Pragma("unroll") for (int k = 0; k < 2; ++k) dst[m][k] = *(const LAS bf16x8*)(lds + PG8_SA(b, h) + aoff + m * 2048 + k * 1024); } while (0)
; #define PG8_LDB(dst, b, h) do { _Pragma("unroll") for (int n = 0; n < 2; ++n) _Pragma("unroll") for (int k = 0; k < 2; ++k) dst[n][k] = *(const LAS bf16x8*)(lds + PG8_SB(b, h) + boff + n * 2048 + k * 1024); } while (0)
; #define PG8_MMA(ai, bj, At, Bt) do { __builtin_amdgcn_s_setprio(1); _Pragma("unroll") for (int m = 0; m < 4; ++m) _Pragma("unroll") for (int n = 0; n < 2; ++n) _Pragma("unroll") for (int k = 0; k < 2; ++k) \
;         acc[ai][bj][m][n] = __builtin_amdgcn_mfma_f32_16x16x32_bf16(Bt[n][k], At[m][k], acc[ai][bj][m][n], 0, 0, 0); __builtin_amdgcn_s_setprio(0); } while (0)
; #define PG8_WAIT_V(n) asm volatile("s_waitcnt vmcnt(" #n ")" ::: "memory")
; #define PG8_WAIT_L(n) asm volatile("s_waitcnt lgkmcnt(" #n ")" ::: "memory")
; #define PG8_BAR __builtin_amdgcn_s_barrier()
; #define PG8_SCHED __builtin_amdgcn_sched_barrier(0)
; template <class Epi, class Sched>
; __device__ __forceinline__ void gemm_phase(LAS unsigned char* lds, const int tid, const Gemm g, const Sched& S, const Epi& E) {
;     ...
;             PG8_LDB(B0, 1, 0); PG8_LDB(B1, 1, 1); PG8_SCHED; PG8_LDA(At, 1, 0); PG8_STAGE(PG8_SA(0, 1), a2 + hstep, voffA);
;             PG8_WAIT_V(8); PG8_WAIT_L(0); PG8_BAR; PG8_MMA(0, 0, At, B0); PG8_MMA(0, 1, At, B1); PG8_BAR; PG8_SCHED;
;             PG8_LDA(At, 1, 1); PG8_STAGE(PG8_SB(1, 0), b3, voffB); PG8_STAGE(PG8_SB(1, 1), b3 + hstep, voffB); PG8_STAGE(PG8_SA(1, 0), a3, voffA);
;             PG8_WAIT_V(8); PG8_WAIT_L(0); PG8_BAR; PG8_MMA(1, 0, At, B0); PG8_MMA(1, 1, At, B1); PG8_BAR; PG8_SCHED;
;         }
	s_setprio 0
	s_add_i32 s29, 0, 0x18000
	s_add_i32 s30, 0, 0x1c000
	v_add_u32_e32 v152, s29, v165
	v_add_u32_e32 v162, s30, v165
	ds_read_b128 v[130:133], v152
	ds_read_b128 v[144:147], v152 offset:1024
	ds_read_b128 v[148:151], v152 offset:2048
	ds_read_b128 v[152:155], v152 offset:3072
	ds_read_b128 v[156:159], v162
	ds_read_b128 v[170:173], v162 offset:1024
	ds_read_b128 v[174:177], v162 offset:2048
	ds_read_b128 v[178:181], v162 offset:3072
	s_add_u32 s48, s62, 0x40000
	s_addc_u32 s49, s63, 0
	s_mov_b32 m0, s36
	ds_read_b128 v[182:185], v169 offset:32768
	ds_read_b128 v[186:189], v169 offset:33792
	ds_read_b128 v[190:193], v169 offset:34816
	ds_read_b128 v[204:207], v169 offset:35840
	ds_read_b128 v[210:213], v169 offset:36864
	ds_read_b128 v[214:217], v169 offset:37888
	ds_read_b128 v[218:221], v169 offset:38912
	ds_read_b128 v[222:225], v169 offset:39936
	global_load_lds_dwordx4 v138, s[48:49]
	s_mov_b32 m0, s37
	s_nop 0
	global_load_lds_dwordx4 v136, s[48:49]
	s_waitcnt vmcnt(8)
	s_waitcnt lgkmcnt(0)
	s_barrier
	s_setprio 1
	v_mfma_f32_16x16x32_bf16 v[126:129], v[130:133], v[182:185], v[126:129]
	v_mfma_f32_16x16x32_bf16 v[122:125], v[148:151], v[182:185], v[122:125]
	v_mfma_f32_16x16x32_bf16 v[118:121], v[130:133], v[190:193], v[118:121]
	v_mfma_f32_16x16x32_bf16 v[110:113], v[148:151], v[190:193], v[110:113]
	v_mfma_f32_16x16x32_bf16 v[102:105], v[130:133], v[210:213], v[102:105]
	v_mfma_f32_16x16x32_bf16 v[94:97], v[148:151], v[210:213], v[94:97]
	v_mfma_f32_16x16x32_bf16 v[86:89], v[130:133], v[218:221], v[86:89]
	v_mfma_f32_16x16x32_bf16 v[78:81], v[148:151], v[218:221], v[78:81]
	v_mfma_f32_16x16x32_bf16 v[126:129], v[144:147], v[186:189], v[126:129]
	v_mfma_f32_16x16x32_bf16 v[122:125], v[152:155], v[186:189], v[122:125]
	v_mfma_f32_16x16x32_bf16 v[118:121], v[144:147], v[204:207], v[118:121]
	v_mfma_f32_16x16x32_bf16 v[110:113], v[152:155], v[204:207], v[110:113]
	v_mfma_f32_16x16x32_bf16 v[102:105], v[144:147], v[214:217], v[102:105]
	v_mfma_f32_16x16x32_bf16 v[94:97], v[152:155], v[214:217], v[94:97]
	v_mfma_f32_16x16x32_bf16 v[86:89], v[144:147], v[222:225], v[86:89]
	v_mfma_f32_16x16x32_bf16 v[78:81], v[152:155], v[222:225], v[78:81]
	v_mfma_f32_16x16x32_bf16 v[114:117], v[156:159], v[182:185], v[114:117]
	v_mfma_f32_16x16x32_bf16 v[106:109], v[174:177], v[182:185], v[106:109]
	v_mfma_f32_16x16x32_bf16 v[98:101], v[156:159], v[190:193], v[98:101]
	v_mfma_f32_16x16x32_bf16 v[90:93], v[174:177], v[190:193], v[90:93]
	v_mfma_f32_16x16x32_bf16 v[82:85], v[156:159], v[210:213], v[82:85]
	v_mfma_f32_16x16x32_bf16 v[74:77], v[174:177], v[210:213], v[74:77]
	v_mfma_f32_16x16x32_bf16 v[70:73], v[156:159], v[218:221], v[70:73]
	v_mfma_f32_16x16x32_bf16 v[66:69], v[174:177], v[218:221], v[66:69]
	v_mfma_f32_16x16x32_bf16 v[114:117], v[170:173], v[186:189], v[114:117]
	v_mfma_f32_16x16x32_bf16 v[106:109], v[178:181], v[186:189], v[106:109]
	v_mfma_f32_16x16x32_bf16 v[98:101], v[170:173], v[204:207], v[98:101]
	v_mfma_f32_16x16x32_bf16 v[90:93], v[178:181], v[204:207], v[90:93]
	v_mfma_f32_16x16x32_bf16 v[82:85], v[170:173], v[214:217], v[82:85]
	v_mfma_f32_16x16x32_bf16 v[74:77], v[178:181], v[214:217], v[74:77]
	v_mfma_f32_16x16x32_bf16 v[70:73], v[170:173], v[222:225], v[70:73]
	v_mfma_f32_16x16x32_bf16 v[66:69], v[178:181], v[222:225], v[66:69]
	s_barrier
	s_setprio 0
	s_add_i32 s29, s29, s12
	s_mov_b32 m0, s29
	ds_read_b128 v[182:185], v169 offset:49152
	ds_read_b128 v[186:189], v169 offset:50176
	ds_read_b128 v[190:193], v169 offset:51200
	ds_read_b128 v[204:207], v169 offset:52224
	ds_read_b128 v[210:213], v169 offset:53248
	ds_read_b128 v[214:217], v169 offset:54272
	ds_read_b128 v[218:221], v169 offset:55296
	ds_read_b128 v[222:225], v169 offset:56320
	global_load_lds_dwordx4 v161, s[20:21]
	s_add_i32 m0, s29, 0x2000
	s_add_i32 s29, s30, s12
	global_load_lds_dwordx4 v195, s[20:21]
	s_add_u32 s20, s20, 0x40080
	s_addc_u32 s21, s21, 0
	s_mov_b32 m0, s29
	s_nop 0
	global_load_lds_dwordx4 v0, s[20:21]
	s_add_i32 m0, s29, 0x2000
	s_nop 0
	global_load_lds_dwordx4 v134, s[20:21]
	s_mov_b32 m0, s38
	s_nop 0
	global_load_lds_dwordx4 v201, s[62:63]
	s_mov_b32 m0, s39
	s_nop 0
	global_load_lds_dwordx4 v227, s[62:63]
	s_waitcnt vmcnt(8)
	s_waitcnt lgkmcnt(0)
	s_barrier
	s_setprio 1
	v_mfma_f32_16x16x32_bf16 v[62:65], v[130:133], v[182:185], v[62:65]
	v_mfma_f32_16x16x32_bf16 v[58:61], v[148:151], v[182:185], v[58:61]
	v_mfma_f32_16x16x32_bf16 v[54:57], v[130:133], v[190:193], v[54:57]
	v_mfma_f32_16x16x32_bf16 v[46:49], v[148:151], v[190:193], v[46:49]
	v_mfma_f32_16x16x32_bf16 v[38:41], v[130:133], v[210:213], v[38:41]
	v_mfma_f32_16x16x32_bf16 v[30:33], v[148:151], v[210:213], v[30:33]
	v_mfma_f32_16x16x32_bf16 v[22:25], v[130:133], v[218:221], v[22:25]
	v_mfma_f32_16x16x32_bf16 v[14:17], v[148:151], v[218:221], v[14:17]
	v_mfma_f32_16x16x32_bf16 v[62:65], v[144:147], v[186:189], v[62:65]
	v_mfma_f32_16x16x32_bf16 v[58:61], v[152:155], v[186:189], v[58:61]
	v_mfma_f32_16x16x32_bf16 v[54:57], v[144:147], v[204:207], v[54:57]
	v_mfma_f32_16x16x32_bf16 v[46:49], v[152:155], v[204:207], v[46:49]
	v_mfma_f32_16x16x32_bf16 v[38:41], v[144:147], v[214:217], v[38:41]
	v_mfma_f32_16x16x32_bf16 v[30:33], v[152:155], v[214:217], v[30:33]
	v_mfma_f32_16x16x32_bf16 v[22:25], v[144:147], v[222:225], v[22:25]
	v_mfma_f32_16x16x32_bf16 v[14:17], v[152:155], v[222:225], v[14:17]
	v_mfma_f32_16x16x32_bf16 v[50:53], v[156:159], v[182:185], v[50:53]
	v_mfma_f32_16x16x32_bf16 v[42:45], v[174:177], v[182:185], v[42:45]
	v_mfma_f32_16x16x32_bf16 v[34:37], v[156:159], v[190:193], v[34:37]
	v_mfma_f32_16x16x32_bf16 v[26:29], v[174:177], v[190:193], v[26:29]
	v_mfma_f32_16x16x32_bf16 v[18:21], v[156:159], v[210:213], v[18:21]
	v_mfma_f32_16x16x32_bf16 v[10:13], v[174:177], v[210:213], v[10:13]
	v_mfma_f32_16x16x32_bf16 v[6:9], v[156:159], v[218:221], v[6:9]
	v_mfma_f32_16x16x32_bf16 v[2:5], v[174:177], v[218:221], v[2:5]
	v_mfma_f32_16x16x32_bf16 v[50:53], v[170:173], v[186:189], v[50:53]
	v_mfma_f32_16x16x32_bf16 v[42:45], v[178:181], v[186:189], v[42:45]
	v_mfma_f32_16x16x32_bf16 v[34:37], v[170:173], v[204:207], v[34:37]
	v_mfma_f32_16x16x32_bf16 v[26:29], v[178:181], v[204:207], v[26:29]
	v_mfma_f32_16x16x32_bf16 v[18:21], v[170:173], v[214:217], v[18:21]
	v_mfma_f32_16x16x32_bf16 v[10:13], v[178:181], v[214:217], v[10:13]
	v_mfma_f32_16x16x32_bf16 v[6:9], v[170:173], v[222:225], v[6:9]
	v_mfma_f32_16x16x32_bf16 v[2:5], v[178:181], v[222:225], v[2:5]
	s_barrier
	s_setprio 0
	s_add_i32 s46, s46, 2
	s_add_u32 s44, s44, 0x100
	s_addc_u32 s45, s45, 0
	s_add_u32 s60, s60, 0x100
	s_addc_u32 s61, s61, 0
	s_cmp_gt_u32 s46, 13
	s_cbranch_scc0 .LBB0_559
	s_and_b64 vcc, exec, s[4:5]
	s_cbranch_vccz .LBB0_562
	s_barrier

;     __device__ bool next(int i, Unit& u) const { if (!b.next(i / 3, u)) return false; u.pz = i % 3; return true; }
; #define PG8_STAGE(bufoff, gbase, voff) do { _Pragma("unroll") for (int _i = 0; _i < 2; ++_i) \
;         __builtin_amdgcn_global_load_lds((const gunsigned*)((const gchar*)(gbase) + (voff)[_i]), (LAS unsigned*)(lds + (bufoff) + ldsw + _i * 8192), 16, 0, 0); } while (0)
; #define PG8_LDA(dst, b, h) do { _Pragma("unroll") for (int m = 0; m < 4; ++m) _Pragma("unroll") for (int k = 0; k < 2; ++k) dst[m][k] = *(const LAS bf16x8*)(lds + PG8_SA(b, h) + aoff + m * 2048 + k * 1024); } while (0)
; #define PG8_LDB(dst, b, h) do { _Pragma("unroll") for (int n = 0; n < 2; ++n) _Pragma("unroll") for (int k = 0; k < 2; ++k) dst[n][k] = *(const LAS bf16x8*)(lds + PG8_SB(b, h) + boff + n * 2048 + k * 1024); } while (0)
; #define PG8_WAIT_V(n) asm volatile("s_waitcnt vmcnt(" #n ")" ::: "memory")
; #define PG8_WAIT_L(n) asm volatile("s_waitcnt lgkmcnt(" #n ")" ::: "memory")
; #define PG8_BAR __builtin_amdgcn_s_barrier()
; template <class Epi, class Sched>
; __device__ __forceinline__ void gemm_phase(LAS unsigned char* lds, const int tid, const Gemm g, const Sched& S, const Epi& E) {
;     ...
;         const bool has_next = S.next(ui + 1, nxt);
;         const gchar* nA = has_next ? (const gchar*)g.A + (size_t)nxt.pm * tstep + (size_t)nxt.pz * g.zA : cA;
;         const gchar* nB = has_next ? (const gchar*)g.Bt + (size_t)nxt.pn * tstep + (size_t)nxt.pz * g.zB : cB;
;         for (int t = 0; t < nt; t += 2) {
;             const bool last = (t == nt - 2);
;             const gchar* a1 = cA + (size_t)(t + 1) * kstep;
;             const gchar* a2 = last ? nA : cA + (size_t)(t + 2) * kstep; const gchar* b2 = last ? nB : cB + (size_t)(t + 2) * kstep;
;             const gchar* a3 = a2 + kstep; const gchar* b3 = b2 + kstep;
;             PG8_LDB(B0, 0, 0); PG8_LDB(B1, 0, 1); PG8_SCHED; PG8_LDA(At, 0, 0); PG8_STAGE(PG8_SA(1, 1), a1 + hstep, voffA);
;             PG8_WAIT_V(8); PG8_WAIT_L(0); PG8_BAR; PG8_MMA(0, 0, At, B0); PG8_MMA(0, 1, At, B1); PG8_BAR; PG8_SCHED;
;             PG8_LDA(At, 0, 1); PG8_STAGE(PG8_SB(0, 0), b2, voffB); PG8_STAGE(PG8_SB(0, 1), b2 + hstep, voffB); PG8_STAGE(PG8_SA(0, 0), a2, voffA);
;             PG8_WAIT_V(8); PG8_WAIT_L(0); PG8_BAR; PG8_MMA(1, 0, At, B0); PG8_MMA(1, 1, At, B1); PG8_BAR; PG8_SCHED;
.LBB0_598:
	s_add_u32 s20, s62, 0x100
	s_addc_u32 s21, s63, 0
	s_add_i32 s29, 0, 0x10000
	s_cmp_eq_u32 s45, 40
	s_cselect_b32 s73, s9, s21
	s_cselect_b32 s72, s8, s20
	s_cselect_b32 s67, s61, s44
	s_cselect_b32 s66, s60, s31
	s_add_i32 s48, 0, 0x14000
	v_add_u32_e32 v142, s29, v210
	v_add_u32_e32 v158, s48, v210
	ds_read_b128 v[130:133], v142
	ds_read_b128 v[134:137], v142 offset:1024
	ds_read_b128 v[138:141], v142 offset:2048
	ds_read_b128 v[142:145], v142 offset:3072
	ds_read_b128 v[146:149], v158
	ds_read_b128 v[150:153], v158 offset:1024
	ds_read_b128 v[154:157], v158 offset:2048
	ds_read_b128 v[158:161], v158 offset:3072
	s_add_i32 m0, s34, 0xc000
	ds_read_b128 v[162:165], v214
	ds_read_b128 v[166:169], v214 offset:1024
	ds_read_b128 v[170:173], v214 offset:2048
	ds_read_b128 v[174:177], v214 offset:3072
	ds_read_b128 v[188:191], v214 offset:4096
	ds_read_b128 v[192:195], v214 offset:5120
	ds_read_b128 v[204:207], v214 offset:6144
	ds_read_b128 v[216:219], v214 offset:7168
	global_load_lds_dwordx4 v186, s[62:63]
	s_add_i32 m0, s34, 0xe000
	s_nop 0
	global_load_lds_dwordx4 v184, s[62:63]
	s_waitcnt vmcnt(8)
	s_waitcnt lgkmcnt(0)
	s_barrier
	s_setprio 1
	v_mfma_f32_16x16x32_bf16 v[126:129], v[130:133], v[162:165], v[126:129]
	v_mfma_f32_16x16x32_bf16 v[122:125], v[138:141], v[162:165], v[122:125]
	v_mfma_f32_16x16x32_bf16 v[110:113], v[130:133], v[170:173], v[110:113]
	v_mfma_f32_16x16x32_bf16 v[106:109], v[138:141], v[170:173], v[106:109]
	v_mfma_f32_16x16x32_bf16 v[94:97], v[130:133], v[188:191], v[94:97]
	v_mfma_f32_16x16x32_bf16 v[90:93], v[138:141], v[188:191], v[90:93]
	v_mfma_f32_16x16x32_bf16 v[78:81], v[130:133], v[204:207], v[78:81]
	v_mfma_f32_16x16x32_bf16 v[74:77], v[138:141], v[204:207], v[74:77]
	v_mfma_f32_16x16x32_bf16 v[126:129], v[134:137], v[166:169], v[126:129]
	v_mfma_f32_16x16x32_bf16 v[122:125], v[142:145], v[166:169], v[122:125]
	v_mfma_f32_16x16x32_bf16 v[110:113], v[134:137], v[174:177], v[110:113]
	v_mfma_f32_16x16x32_bf16 v[106:109], v[142:145], v[174:177], v[106:109]
	v_mfma_f32_16x16x32_bf16 v[94:97], v[134:137], v[192:195], v[94:97]
	v_mfma_f32_16x16x32_bf16 v[90:93], v[142:145], v[192:195], v[90:93]
	v_mfma_f32_16x16x32_bf16 v[78:81], v[134:137], v[216:219], v[78:81]
	v_mfma_f32_16x16x32_bf16 v[74:77], v[142:145], v[216:219], v[74:77]
	v_mfma_f32_16x16x32_bf16 v[118:121], v[146:149], v[162:165], v[118:121]
	v_mfma_f32_16x16x32_bf16 v[114:117], v[154:157], v[162:165], v[114:117]
	v_mfma_f32_16x16x32_bf16 v[102:105], v[146:149], v[170:173], v[102:105]
	v_mfma_f32_16x16x32_bf16 v[98:101], v[154:157], v[170:173], v[98:101]
	v_mfma_f32_16x16x32_bf16 v[86:89], v[146:149], v[188:191], v[86:89]
	v_mfma_f32_16x16x32_bf16 v[82:85], v[154:157], v[188:191], v[82:85]
	v_mfma_f32_16x16x32_bf16 v[70:73], v[146:149], v[204:207], v[70:73]
	v_mfma_f32_16x16x32_bf16 v[66:69], v[154:157], v[204:207], v[66:69]
	v_mfma_f32_16x16x32_bf16 v[118:121], v[150:153], v[166:169], v[118:121]
	v_mfma_f32_16x16x32_bf16 v[114:117], v[158:161], v[166:169], v[114:117]
	v_mfma_f32_16x16x32_bf16 v[102:105], v[150:153], v[174:177], v[102:105]
	v_mfma_f32_16x16x32_bf16 v[98:101], v[158:161], v[174:177], v[98:101]
	v_mfma_f32_16x16x32_bf16 v[86:89], v[150:153], v[192:195], v[86:89]
	v_mfma_f32_16x16x32_bf16 v[82:85], v[158:161], v[192:195], v[82:85]
	v_mfma_f32_16x16x32_bf16 v[70:73], v[150:153], v[216:219], v[70:73]
	v_mfma_f32_16x16x32_bf16 v[66:69], v[158:161], v[216:219], v[66:69]
	s_barrier
	s_setprio 0
	s_add_i32 s29, s29, s15
	s_mov_b32 m0, s29
	ds_read_b128 v[162:165], v214 offset:16384
	ds_read_b128 v[166:169], v214 offset:17408
	ds_read_b128 v[170:173], v214 offset:18432
	ds_read_b128 v[174:177], v214 offset:19456
	ds_read_b128 v[188:191], v214 offset:20480
	ds_read_b128 v[192:195], v214 offset:21504
	ds_read_b128 v[204:207], v214 offset:22528
	ds_read_b128 v[216:219], v214 offset:23552
	global_load_lds_dwordx4 v0, s[66:67]
	s_add_i32 m0, s29, 0x2000
	s_add_u32 s46, s66, 0xb0000
	s_addc_u32 s47, s67, 0
	s_add_i32 s29, s48, s15
	global_load_lds_dwordx4 v182, s[66:67]
	s_mov_b32 m0, s29
	s_nop 0
	global_load_lds_dwordx4 v0, s[46:47]
	s_add_i32 m0, s29, 0x2000
	s_nop 0
	global_load_lds_dwordx4 v182, s[46:47]
	s_mov_b32 m0, s34
	s_nop 0
	global_load_lds_dwordx4 v178, s[72:73]
	s_mov_b32 m0, s12
	s_nop 0
	global_load_lds_dwordx4 v180, s[72:73]
	s_waitcnt vmcnt(8)
	s_waitcnt lgkmcnt(0)
	s_barrier
	s_setprio 1
	v_mfma_f32_16x16x32_bf16 v[62:65], v[130:133], v[162:165], v[62:65]
	v_mfma_f32_16x16x32_bf16 v[58:61], v[138:141], v[162:165], v[58:61]
	v_mfma_f32_16x16x32_bf16 v[46:49], v[130:133], v[170:173], v[46:49]
	v_mfma_f32_16x16x32_bf16 v[42:45], v[138:141], v[170:173], v[42:45]
	v_mfma_f32_16x16x32_bf16 v[30:33], v[130:133], v[188:191], v[30:33]
	v_mfma_f32_16x16x32_bf16 v[26:29], v[138:141], v[188:191], v[26:29]
	v_mfma_f32_16x16x32_bf16 v[14:17], v[130:133], v[204:207], v[14:17]
	v_mfma_f32_16x16x32_bf16 v[10:13], v[138:141], v[204:207], v[10:13]
	v_mfma_f32_16x16x32_bf16 v[62:65], v[134:137], v[166:169], v[62:65]
	v_mfma_f32_16x16x32_bf16 v[58:61], v[142:145], v[166:169], v[58:61]
	v_mfma_f32_16x16x32_bf16 v[46:49], v[134:137], v[174:177], v[46:49]
	v_mfma_f32_16x16x32_bf16 v[42:45], v[142:145], v[174:177], v[42:45]
	v_mfma_f32_16x16x32_bf16 v[30:33], v[134:137], v[192:195], v[30:33]
	v_mfma_f32_16x16x32_bf16 v[26:29], v[142:145], v[192:195], v[26:29]
	v_mfma_f32_16x16x32_bf16 v[14:17], v[134:137], v[216:219], v[14:17]
	v_mfma_f32_16x16x32_bf16 v[10:13], v[142:145], v[216:219], v[10:13]
	v_mfma_f32_16x16x32_bf16 v[54:57], v[146:149], v[162:165], v[54:57]
	v_mfma_f32_16x16x32_bf16 v[50:53], v[154:157], v[162:165], v[50:53]
	v_mfma_f32_16x16x32_bf16 v[38:41], v[146:149], v[170:173], v[38:41]
	v_mfma_f32_16x16x32_bf16 v[34:37], v[154:157], v[170:173], v[34:37]
	v_mfma_f32_16x16x32_bf16 v[22:25], v[146:149], v[188:191], v[22:25]
	v_mfma_f32_16x16x32_bf16 v[18:21], v[154:157], v[188:191], v[18:21]
	v_mfma_f32_16x16x32_bf16 v[6:9], v[146:149], v[204:207], v[6:9]
	v_mfma_f32_16x16x32_bf16 v[2:5], v[154:157], v[204:207], v[2:5]
	v_mfma_f32_16x16x32_bf16 v[54:57], v[150:153], v[166:169], v[54:57]
	v_mfma_f32_16x16x32_bf16 v[50:53], v[158:161], v[166:169], v[50:53]
	v_mfma_f32_16x16x32_bf16 v[38:41], v[150:153], v[174:177], v[38:41]
	v_mfma_f32_16x16x32_bf16 v[34:37], v[158:161], v[174:177], v[34:37]
	v_mfma_f32_16x16x32_bf16 v[22:25], v[150:153], v[192:195], v[22:25]
	v_mfma_f32_16x16x32_bf16 v[18:21], v[158:161], v[192:195], v[18:21]
	v_mfma_f32_16x16x32_bf16 v[6:9], v[150:153], v[216:219], v[6:9]
	v_mfma_f32_16x16x32_bf16 v[2:5], v[158:161], v[216:219], v[2:5]
	s_barrier
; #define PG8_STAGE(bufoff, gbase, voff) do { _Pragma("unroll") for (int _i = 0; _i < 2; ++_i) \
;         __builtin_amdgcn_global_load_lds((const gunsigned*)((const gchar*)(gbase) + (voff)[_i]), (LAS unsigned*)(lds + (bufoff) + ldsw + _i * 8192), 16, 0, 0); } while (0)
; #define PG8_LDA(dst, b, h) do { _Pragma("unroll") for (int m = 0; m < 4; ++m) _Pragma("unroll") for (int k = 0; k < 2; ++k) dst[m][k] = *(const LAS bf16x8*)(lds + PG8_SA(b, h) + aoff + m * 2048 + k * 1024); } while (0)
; #define PG8_LDB(dst, b, h) do { _Pragma("unroll") for (int n = 0; n < 2; ++n) _Pragma("unroll") for (int k = 0; k < 2; ++k) dst[n][k] = *(const LAS bf16x8*)(lds + PG8_SB(b, h) + boff + n * 2048 + k * 1024); } while (0)
; #define PG8_MMA(ai, bj, At, Bt) do { __builtin_amdgcn_s_setprio(1); _Pragma("unroll") for (int m = 0; m < 4; ++m) _Pragma("unroll") for (int n = 0; n < 2; ++n) _Pragma("unroll") for (int k = 0; k < 2; ++k) \
;         acc[ai][bj][m][n] = __builtin_amdgcn_mfma_f32_16x16x32_bf16(Bt[n][k], At[m][k], acc[ai][bj][m][n], 0, 0, 0); __builtin_amdgcn_s_setprio(0); } while (0)
; #define PG8_WAIT_V(n) asm volatile("s_waitcnt vmcnt(" #n ")" ::: "memory")
; #define PG8_WAIT_L(n) asm volatile("s_waitcnt lgkmcnt(" #n ")" ::: "memory")
; #define PG8_BAR __builtin_amdgcn_s_barrier()
; #define PG8_SCHED __builtin_amdgcn_sched_barrier(0)
; template <class Epi, class Sched>
; __device__ __forceinline__ void gemm_phase(LAS unsigned char* lds, const int tid, const Gemm g, const Sched& S, const Epi& E) {
;     ...
;             PG8_LDB(B0, 1, 0); PG8_LDB(B1, 1, 1); PG8_SCHED; PG8_LDA(At, 1, 0); PG8_STAGE(PG8_SA(0, 1), a2 + hstep, voffA);
;             PG8_WAIT_V(8); PG8_WAIT_L(0); PG8_BAR; PG8_MMA(0, 0, At, B0); PG8_MMA(0, 1, At, B1); PG8_BAR; PG8_SCHED;
;             PG8_LDA(At, 1, 1); PG8_STAGE(PG8_SB(1, 0), b3, voffB); PG8_STAGE(PG8_SB(1, 1), b3 + hstep, voffB); PG8_STAGE(PG8_SA(1, 0), a3, voffA);
;             PG8_WAIT_V(8); PG8_WAIT_L(0); PG8_BAR; PG8_MMA(1, 0, At, B0); PG8_MMA(1, 1, At, B1); PG8_BAR; PG8_SCHED;
;         }
	s_setprio 0
	s_add_i32 s29, 0, 0x18000
	s_add_i32 s48, 0, 0x1c000
	v_add_u32_e32 v142, s29, v210
	v_add_u32_e32 v158, s48, v210
	ds_read_b128 v[130:133], v142
	ds_read_b128 v[134:137], v142 offset:1024
	ds_read_b128 v[138:141], v142 offset:2048
	ds_read_b128 v[142:145], v142 offset:3072
	ds_read_b128 v[146:149], v158
	ds_read_b128 v[150:153], v158 offset:1024
	ds_read_b128 v[154:157], v158 offset:2048
	ds_read_b128 v[158:161], v158 offset:3072
	s_add_u32 s46, s72, 0xb0000
	s_addc_u32 s47, s73, 0
	s_mov_b32 m0, s35
	ds_read_b128 v[162:165], v214 offset:32768
	ds_read_b128 v[166:169], v214 offset:33792
	ds_read_b128 v[170:173], v214 offset:34816
	ds_read_b128 v[174:177], v214 offset:35840
	ds_read_b128 v[188:191], v214 offset:36864
	ds_read_b128 v[192:195], v214 offset:37888
	ds_read_b128 v[204:207], v214 offset:38912
	ds_read_b128 v[216:219], v214 offset:39936
	global_load_lds_dwordx4 v178, s[46:47]
	s_mov_b32 m0, s36
	s_nop 0
	global_load_lds_dwordx4 v180, s[46:47]
	s_waitcnt vmcnt(8)
	s_waitcnt lgkmcnt(0)
	s_barrier
	s_setprio 1
	v_mfma_f32_16x16x32_bf16 v[126:129], v[130:133], v[162:165], v[126:129]
	v_mfma_f32_16x16x32_bf16 v[122:125], v[138:141], v[162:165], v[122:125]
	v_mfma_f32_16x16x32_bf16 v[110:113], v[130:133], v[170:173], v[110:113]
	v_mfma_f32_16x16x32_bf16 v[106:109], v[138:141], v[170:173], v[106:109]
	v_mfma_f32_16x16x32_bf16 v[94:97], v[130:133], v[188:191], v[94:97]
	v_mfma_f32_16x16x32_bf16 v[90:93], v[138:141], v[188:191], v[90:93]
	v_mfma_f32_16x16x32_bf16 v[78:81], v[130:133], v[204:207], v[78:81]
	v_mfma_f32_16x16x32_bf16 v[74:77], v[138:141], v[204:207], v[74:77]
	v_mfma_f32_16x16x32_bf16 v[126:129], v[134:137], v[166:169], v[126:129]
	v_mfma_f32_16x16x32_bf16 v[122:125], v[142:145], v[166:169], v[122:125]
	v_mfma_f32_16x16x32_bf16 v[110:113], v[134:137], v[174:177], v[110:113]
	v_mfma_f32_16x16x32_bf16 v[106:109], v[142:145], v[174:177], v[106:109]
	v_mfma_f32_16x16x32_bf16 v[94:97], v[134:137], v[192:195], v[94:97]
	v_mfma_f32_16x16x32_bf16 v[90:93], v[142:145], v[192:195], v[90:93]
	v_mfma_f32_16x16x32_bf16 v[78:81], v[134:137], v[216:219], v[78:81]
	v_mfma_f32_16x16x32_bf16 v[74:77], v[142:145], v[216:219], v[74:77]
	v_mfma_f32_16x16x32_bf16 v[118:121], v[146:149], v[162:165], v[118:121]
	v_mfma_f32_16x16x32_bf16 v[114:117], v[154:157], v[162:165], v[114:117]
	v_mfma_f32_16x16x32_bf16 v[102:105], v[146:149], v[170:173], v[102:105]
	v_mfma_f32_16x16x32_bf16 v[98:101], v[154:157], v[170:173], v[98:101]
	v_mfma_f32_16x16x32_bf16 v[86:89], v[146:149], v[188:191], v[86:89]
	v_mfma_f32_16x16x32_bf16 v[82:85], v[154:157], v[188:191], v[82:85]
	v_mfma_f32_16x16x32_bf16 v[70:73], v[146:149], v[204:207], v[70:73]
	v_mfma_f32_16x16x32_bf16 v[66:69], v[154:157], v[204:207], v[66:69]
	v_mfma_f32_16x16x32_bf16 v[118:121], v[150:153], v[166:169], v[118:121]
	v_mfma_f32_16x16x32_bf16 v[114:117], v[158:161], v[166:169], v[114:117]
	v_mfma_f32_16x16x32_bf16 v[102:105], v[150:153], v[174:177], v[102:105]
	v_mfma_f32_16x16x32_bf16 v[98:101], v[158:161], v[174:177], v[98:101]
	v_mfma_f32_16x16x32_bf16 v[86:89], v[150:153], v[192:195], v[86:89]
	v_mfma_f32_16x16x32_bf16 v[82:85], v[158:161], v[192:195], v[82:85]
	v_mfma_f32_16x16x32_bf16 v[70:73], v[150:153], v[216:219], v[70:73]
	v_mfma_f32_16x16x32_bf16 v[66:69], v[158:161], v[216:219], v[66:69]
	s_barrier
	s_setprio 0
	s_add_i32 s29, s29, s15
	s_mov_b32 m0, s29
	ds_read_b128 v[162:165], v214 offset:49152
	ds_read_b128 v[166:169], v214 offset:50176
	ds_read_b128 v[170:173], v214 offset:51200
	ds_read_b128 v[174:177], v214 offset:52224
	ds_read_b128 v[188:191], v214 offset:53248
	ds_read_b128 v[192:195], v214 offset:54272
	ds_read_b128 v[204:207], v214 offset:55296
	ds_read_b128 v[216:219], v214 offset:56320
	global_load_lds_dwordx4 v221, s[66:67]
	s_add_i32 m0, s29, 0x2000
	s_add_u32 s46, s66, 0xb0080
	s_addc_u32 s47, s67, 0
	s_add_i32 s29, s48, s15
	global_load_lds_dwordx4 v223, s[66:67]
	s_mov_b32 m0, s29
	s_nop 0
	global_load_lds_dwordx4 v0, s[46:47]
	s_add_i32 m0, s29, 0x2000
	s_nop 0
	global_load_lds_dwordx4 v182, s[46:47]
	s_mov_b32 m0, s37
	s_nop 0
	global_load_lds_dwordx4 v225, s[72:73]
	s_mov_b32 m0, s38
	s_nop 0
	global_load_lds_dwordx4 v227, s[72:73]
	s_waitcnt vmcnt(8)
	s_waitcnt lgkmcnt(0)
	s_barrier
	s_setprio 1
	v_mfma_f32_16x16x32_bf16 v[62:65], v[130:133], v[162:165], v[62:65]
	v_mfma_f32_16x16x32_bf16 v[58:61], v[138:141], v[162:165], v[58:61]
	v_mfma_f32_16x16x32_bf16 v[46:49], v[130:133], v[170:173], v[46:49]
	v_mfma_f32_16x16x32_bf16 v[42:45], v[138:141], v[170:173], v[42:45]
	v_mfma_f32_16x16x32_bf16 v[30:33], v[130:133], v[188:191], v[30:33]
	v_mfma_f32_16x16x32_bf16 v[26:29], v[138:141], v[188:191], v[26:29]
	v_mfma_f32_16x16x32_bf16 v[14:17], v[130:133], v[204:207], v[14:17]
	v_mfma_f32_16x16x32_bf16 v[10:13], v[138:141], v[204:207], v[10:13]
	v_mfma_f32_16x16x32_bf16 v[62:65], v[134:137], v[166:169], v[62:65]
	v_mfma_f32_16x16x32_bf16 v[58:61], v[142:145], v[166:169], v[58:61]
	v_mfma_f32_16x16x32_bf16 v[46:49], v[134:137], v[174:177], v[46:49]
	v_mfma_f32_16x16x32_bf16 v[42:45], v[142:145], v[174:177], v[42:45]
	v_mfma_f32_16x16x32_bf16 v[30:33], v[134:137], v[192:195], v[30:33]
	v_mfma_f32_16x16x32_bf16 v[26:29], v[142:145], v[192:195], v[26:29]
	v_mfma_f32_16x16x32_bf16 v[14:17], v[134:137], v[216:219], v[14:17]
	v_mfma_f32_16x16x32_bf16 v[10:13], v[142:145], v[216:219], v[10:13]
	v_mfma_f32_16x16x32_bf16 v[54:57], v[146:149], v[162:165], v[54:57]
	v_mfma_f32_16x16x32_bf16 v[50:53], v[154:157], v[162:165], v[50:53]
	v_mfma_f32_16x16x32_bf16 v[38:41], v[146:149], v[170:173], v[38:41]
	v_mfma_f32_16x16x32_bf16 v[34:37], v[154:157], v[170:173], v[34:37]
	v_mfma_f32_16x16x32_bf16 v[22:25], v[146:149], v[188:191], v[22:25]
	v_mfma_f32_16x16x32_bf16 v[18:21], v[154:157], v[188:191], v[18:21]
	v_mfma_f32_16x16x32_bf16 v[6:9], v[146:149], v[204:207], v[6:9]
	v_mfma_f32_16x16x32_bf16 v[2:5], v[154:157], v[204:207], v[2:5]
	v_mfma_f32_16x16x32_bf16 v[54:57], v[150:153], v[166:169], v[54:57]
	v_mfma_f32_16x16x32_bf16 v[50:53], v[158:161], v[166:169], v[50:53]
	v_mfma_f32_16x16x32_bf16 v[38:41], v[150:153], v[174:177], v[38:41]
	v_mfma_f32_16x16x32_bf16 v[34:37], v[158:161], v[174:177], v[34:37]
	v_mfma_f32_16x16x32_bf16 v[22:25], v[150:153], v[192:195], v[22:25]
	v_mfma_f32_16x16x32_bf16 v[18:21], v[158:161], v[192:195], v[18:21]
	v_mfma_f32_16x16x32_bf16 v[6:9], v[150:153], v[216:219], v[6:9]
	v_mfma_f32_16x16x32_bf16 v[2:5], v[158:161], v[216:219], v[2:5]
	s_barrier
	s_setprio 0
	s_add_i32 s45, s45, 2
	s_add_u32 s31, s31, 0x100
	s_addc_u32 s44, s44, 0
	s_cmp_gt_u32 s45, 41
	s_mov_b64 s[62:63], s[20:21]
	s_cbranch_scc0 .LBB0_598
	s_and_b64 vcc, exec, s[58:59]
	s_cbranch_vccz .LBB0_601
	s_barrier

;     __device__ bool next(int i, Unit& u) const { if (!b.next(i / 3, u)) return false; u.pz = i % 3; return true; }
; #define PG8_STAGE(bufoff, gbase, voff) do { _Pragma("unroll") for (int _i = 0; _i < 2; ++_i) \
;         __builtin_amdgcn_global_load_lds((const gunsigned*)((const gchar*)(gbase) + (voff)[_i]), (LAS unsigned*)(lds + (bufoff) + ldsw + _i * 8192), 16, 0, 0); } while (0)
; #define PG8_LDA(dst, b, h) do { _Pragma("unroll") for (int m = 0; m < 4; ++m) _Pragma("unroll") for (int k = 0; k < 2; ++k) dst[m][k] = *(const LAS bf16x8*)(lds + PG8_SA(b, h) + aoff + m * 2048 + k * 1024); } while (0)
; #define PG8_LDB(dst, b, h) do { _Pragma("unroll") for (int n = 0; n < 2; ++n) _Pragma("unroll") for (int k = 0; k < 2; ++k) dst[n][k] = *(const LAS bf16x8*)(lds + PG8_SB(b, h) + boff + n * 2048 + k * 1024); } while (0)
; #define PG8_WAIT_V(n) asm volatile("s_waitcnt vmcnt(" #n ")" ::: "memory")
; #define PG8_WAIT_L(n) asm volatile("s_waitcnt lgkmcnt(" #n ")" ::: "memory")
; #define PG8_BAR __builtin_amdgcn_s_barrier()
; template <class Epi, class Sched>
; __device__ __forceinline__ void gemm_phase(LAS unsigned char* lds, const int tid, const Gemm g, const Sched& S, const Epi& E) {
;     ...
;         const bool has_next = S.next(ui + 1, nxt);
;         const gchar* nA = has_next ? (const gchar*)g.A + (size_t)nxt.pm * tstep + (size_t)nxt.pz * g.zA : cA;
;         const gchar* nB = has_next ? (const gchar*)g.Bt + (size_t)nxt.pn * tstep + (size_t)nxt.pz * g.zB : cB;
;         for (int t = 0; t < nt; t += 2) {
;             const bool last = (t == nt - 2);
;             const gchar* a1 = cA + (size_t)(t + 1) * kstep;
;             const gchar* a2 = last ? nA : cA + (size_t)(t + 2) * kstep; const gchar* b2 = last ? nB : cB + (size_t)(t + 2) * kstep;
;             const gchar* a3 = a2 + kstep; const gchar* b3 = b2 + kstep;
;             PG8_LDB(B0, 0, 0); PG8_LDB(B1, 0, 1); PG8_SCHED; PG8_LDA(At, 0, 0); PG8_STAGE(PG8_SA(1, 1), a1 + hstep, voffA);
;             PG8_WAIT_V(8); PG8_WAIT_L(0); PG8_BAR; PG8_MMA(0, 0, At, B0); PG8_MMA(0, 1, At, B1); PG8_BAR; PG8_SCHED;
;             PG8_LDA(At, 0, 1); PG8_STAGE(PG8_SB(0, 0), b2, voffB); PG8_STAGE(PG8_SB(0, 1), b2 + hstep, voffB); PG8_STAGE(PG8_SA(0, 0), a2, voffA);
;             PG8_WAIT_V(8); PG8_WAIT_L(0); PG8_BAR; PG8_MMA(1, 0, At, B0); PG8_MMA(1, 1, At, B1); PG8_BAR; PG8_SCHED;
.LBB0_647:
	s_add_u32 s20, s58, 0xfffc0080
	s_addc_u32 s21, s59, -1
	s_add_i32 s42, 0, 0x10000
	s_cmp_eq_u32 s41, 12
	s_cselect_b32 s61, s9, s21
	s_cselect_b32 s60, s37, s20
	v_add_u32_e32 v140, s42, v143
	s_cselect_b32 s21, s7, s40
	s_cselect_b32 s20, s38, s39
	s_add_i32 s44, 0, 0x14000
	ds_read_b128 v[146:149], v140
	ds_read_b128 v[150:153], v140 offset:1024
	ds_read_b128 v[154:157], v140 offset:2048
	ds_read_b128 v[158:161], v140 offset:3072
	v_add_u32_e32 v140, s44, v143
	ds_read_b128 v[162:165], v140
	ds_read_b128 v[166:169], v140 offset:1024
	ds_read_b128 v[170:173], v140 offset:2048
	ds_read_b128 v[174:177], v140 offset:3072
	s_add_i32 m0, s23, 0xc000
	ds_read_b128 v[178:181], v145
	ds_read_b128 v[182:185], v145 offset:1024
	ds_read_b128 v[186:189], v145 offset:2048
	ds_read_b128 v[190:193], v145 offset:3072
	ds_read_b128 v[204:207], v145 offset:4096
	ds_read_b128 v[208:211], v145 offset:5120
	ds_read_b128 v[212:215], v145 offset:6144
	ds_read_b128 v[216:219], v145 offset:7168
	global_load_lds_dwordx4 v138, s[58:59]
	s_add_i32 m0, s23, 0xe000
	s_nop 0
	global_load_lds_dwordx4 v136, s[58:59]
	s_waitcnt vmcnt(8)
	s_waitcnt lgkmcnt(0)
	s_barrier
	s_setprio 1
	v_mfma_f32_16x16x32_bf16 v[126:129], v[146:149], v[178:181], v[126:129]
	v_mfma_f32_16x16x32_bf16 v[122:125], v[154:157], v[178:181], v[122:125]
	v_mfma_f32_16x16x32_bf16 v[110:113], v[146:149], v[186:189], v[110:113]
	v_mfma_f32_16x16x32_bf16 v[106:109], v[154:157], v[186:189], v[106:109]
	v_mfma_f32_16x16x32_bf16 v[94:97], v[146:149], v[204:207], v[94:97]
	v_mfma_f32_16x16x32_bf16 v[90:93], v[154:157], v[204:207], v[90:93]
	v_mfma_f32_16x16x32_bf16 v[78:81], v[146:149], v[212:215], v[78:81]
	v_mfma_f32_16x16x32_bf16 v[74:77], v[154:157], v[212:215], v[74:77]
	v_mfma_f32_16x16x32_bf16 v[126:129], v[150:153], v[182:185], v[126:129]
	v_mfma_f32_16x16x32_bf16 v[122:125], v[158:161], v[182:185], v[122:125]
	v_mfma_f32_16x16x32_bf16 v[110:113], v[150:153], v[190:193], v[110:113]
	v_mfma_f32_16x16x32_bf16 v[106:109], v[158:161], v[190:193], v[106:109]
	v_mfma_f32_16x16x32_bf16 v[94:97], v[150:153], v[208:211], v[94:97]
	v_mfma_f32_16x16x32_bf16 v[90:93], v[158:161], v[208:211], v[90:93]
	v_mfma_f32_16x16x32_bf16 v[78:81], v[150:153], v[216:219], v[78:81]
	v_mfma_f32_16x16x32_bf16 v[74:77], v[158:161], v[216:219], v[74:77]
	v_mfma_f32_16x16x32_bf16 v[118:121], v[162:165], v[178:181], v[118:121]
	v_mfma_f32_16x16x32_bf16 v[114:117], v[170:173], v[178:181], v[114:117]
	v_mfma_f32_16x16x32_bf16 v[102:105], v[162:165], v[186:189], v[102:105]
	v_mfma_f32_16x16x32_bf16 v[98:101], v[170:173], v[186:189], v[98:101]
	v_mfma_f32_16x16x32_bf16 v[86:89], v[162:165], v[204:207], v[86:89]
	v_mfma_f32_16x16x32_bf16 v[82:85], v[170:173], v[204:207], v[82:85]
	v_mfma_f32_16x16x32_bf16 v[70:73], v[162:165], v[212:215], v[70:73]
	v_mfma_f32_16x16x32_bf16 v[66:69], v[170:173], v[212:215], v[66:69]
	v_mfma_f32_16x16x32_bf16 v[118:121], v[166:169], v[182:185], v[118:121]
	v_mfma_f32_16x16x32_bf16 v[114:117], v[174:177], v[182:185], v[114:117]
	v_mfma_f32_16x16x32_bf16 v[102:105], v[166:169], v[190:193], v[102:105]
	v_mfma_f32_16x16x32_bf16 v[98:101], v[174:177], v[190:193], v[98:101]
	v_mfma_f32_16x16x32_bf16 v[86:89], v[166:169], v[208:211], v[86:89]
	v_mfma_f32_16x16x32_bf16 v[82:85], v[174:177], v[208:211], v[82:85]
	v_mfma_f32_16x16x32_bf16 v[70:73], v[166:169], v[216:219], v[70:73]
	v_mfma_f32_16x16x32_bf16 v[66:69], v[174:177], v[216:219], v[66:69]
	s_barrier
	s_setprio 0
	s_add_i32 s42, s42, s12
	s_mov_b32 m0, s42
	ds_read_b128 v[178:181], v145 offset:16384
	ds_read_b128 v[182:185], v145 offset:17408
	ds_read_b128 v[186:189], v145 offset:18432
	ds_read_b128 v[190:193], v145 offset:19456
	ds_read_b128 v[204:207], v145 offset:20480
	ds_read_b128 v[208:211], v145 offset:21504
	ds_read_b128 v[212:215], v145 offset:22528
	ds_read_b128 v[216:219], v145 offset:23552
	global_load_lds_dwordx4 v0, s[20:21]
	s_add_i32 m0, s42, 0x2000
	s_add_u32 s42, s20, 0x40000
	s_addc_u32 s43, s21, 0
	s_add_i32 s44, s44, s12
	global_load_lds_dwordx4 v130, s[20:21]
	s_mov_b32 m0, s44
	s_nop 0
	global_load_lds_dwordx4 v0, s[42:43]
	s_add_i32 m0, s44, 0x2000
	s_nop 0
	global_load_lds_dwordx4 v130, s[42:43]
	s_mov_b32 m0, s23
	s_nop 0
	global_load_lds_dwordx4 v134, s[60:61]
	s_mov_b32 m0, s24
	s_nop 0
	global_load_lds_dwordx4 v132, s[60:61]
	s_waitcnt vmcnt(8)
	s_waitcnt lgkmcnt(0)
	s_barrier
	s_setprio 1
	v_mfma_f32_16x16x32_bf16 v[62:65], v[146:149], v[178:181], v[62:65]
	v_mfma_f32_16x16x32_bf16 v[58:61], v[154:157], v[178:181], v[58:61]
	v_mfma_f32_16x16x32_bf16 v[46:49], v[146:149], v[186:189], v[46:49]
	v_mfma_f32_16x16x32_bf16 v[42:45], v[154:157], v[186:189], v[42:45]
	v_mfma_f32_16x16x32_bf16 v[30:33], v[146:149], v[204:207], v[30:33]
	v_mfma_f32_16x16x32_bf16 v[26:29], v[154:157], v[204:207], v[26:29]
	v_mfma_f32_16x16x32_bf16 v[14:17], v[146:149], v[212:215], v[14:17]
	v_mfma_f32_16x16x32_bf16 v[10:13], v[154:157], v[212:215], v[10:13]
	v_mfma_f32_16x16x32_bf16 v[62:65], v[150:153], v[182:185], v[62:65]
	v_mfma_f32_16x16x32_bf16 v[58:61], v[158:161], v[182:185], v[58:61]
	v_mfma_f32_16x16x32_bf16 v[46:49], v[150:153], v[190:193], v[46:49]
	v_mfma_f32_16x16x32_bf16 v[42:45], v[158:161], v[190:193], v[42:45]
	v_mfma_f32_16x16x32_bf16 v[30:33], v[150:153], v[208:211], v[30:33]
	v_mfma_f32_16x16x32_bf16 v[26:29], v[158:161], v[208:211], v[26:29]
	v_mfma_f32_16x16x32_bf16 v[14:17], v[150:153], v[216:219], v[14:17]
	v_mfma_f32_16x16x32_bf16 v[10:13], v[158:161], v[216:219], v[10:13]
	v_mfma_f32_16x16x32_bf16 v[54:57], v[162:165], v[178:181], v[54:57]
	v_mfma_f32_16x16x32_bf16 v[50:53], v[170:173], v[178:181], v[50:53]
	v_mfma_f32_16x16x32_bf16 v[38:41], v[162:165], v[186:189], v[38:41]
	v_mfma_f32_16x16x32_bf16 v[34:37], v[170:173], v[186:189], v[34:37]
	v_mfma_f32_16x16x32_bf16 v[22:25], v[162:165], v[204:207], v[22:25]
	v_mfma_f32_16x16x32_bf16 v[18:21], v[170:173], v[204:207], v[18:21]
	v_mfma_f32_16x16x32_bf16 v[6:9], v[162:165], v[212:215], v[6:9]
	v_mfma_f32_16x16x32_bf16 v[2:5], v[170:173], v[212:215], v[2:5]
	v_mfma_f32_16x16x32_bf16 v[54:57], v[166:169], v[182:185], v[54:57]
	v_mfma_f32_16x16x32_bf16 v[50:53], v[174:177], v[182:185], v[50:53]
	v_mfma_f32_16x16x32_bf16 v[38:41], v[166:169], v[190:193], v[38:41]
	v_mfma_f32_16x16x32_bf16 v[34:37], v[174:177], v[190:193], v[34:37]
	v_mfma_f32_16x16x32_bf16 v[22:25], v[166:169], v[208:211], v[22:25]
	v_mfma_f32_16x16x32_bf16 v[18:21], v[174:177], v[208:211], v[18:21]
	v_mfma_f32_16x16x32_bf16 v[6:9], v[166:169], v[216:219], v[6:9]
	v_mfma_f32_16x16x32_bf16 v[2:5], v[174:177], v[216:219], v[2:5]
	s_barrier
; #define PG8_STAGE(bufoff, gbase, voff) do { _Pragma("unroll") for (int _i = 0; _i < 2; ++_i) \
;         __builtin_amdgcn_global_load_lds((const gunsigned*)((const gchar*)(gbase) + (voff)[_i]), (LAS unsigned*)(lds + (bufoff) + ldsw + _i * 8192), 16, 0, 0); } while (0)
; #define PG8_LDA(dst, b, h) do { _Pragma("unroll") for (int m = 0; m < 4; ++m) _Pragma("unroll") for (int k = 0; k < 2; ++k) dst[m][k] = *(const LAS bf16x8*)(lds + PG8_SA(b, h) + aoff + m * 2048 + k * 1024); } while (0)
; #define PG8_LDB(dst, b, h) do { _Pragma("unroll") for (int n = 0; n < 2; ++n) _Pragma("unroll") for (int k = 0; k < 2; ++k) dst[n][k] = *(const LAS bf16x8*)(lds + PG8_SB(b, h) + boff + n * 2048 + k * 1024); } while (0)
; #define PG8_MMA(ai, bj, At, Bt) do { __builtin_amdgcn_s_setprio(1); _Pragma("unroll") for (int m = 0; m < 4; ++m) _Pragma("unroll") for (int n = 0; n < 2; ++n) _Pragma("unroll") for (int k = 0; k < 2; ++k) \
;         acc[ai][bj][m][n] = __builtin_amdgcn_mfma_f32_16x16x32_bf16(Bt[n][k], At[m][k], acc[ai][bj][m][n], 0, 0, 0); __builtin_amdgcn_s_setprio(0); } while (0)
; #define PG8_WAIT_V(n) asm volatile("s_waitcnt vmcnt(" #n ")" ::: "memory")
; #define PG8_WAIT_L(n) asm volatile("s_waitcnt lgkmcnt(" #n ")" ::: "memory")
; #define PG8_BAR __builtin_amdgcn_s_barrier()
; #define PG8_SCHED __builtin_amdgcn_sched_barrier(0)
; template <class Epi, class Sched>
; __device__ __forceinline__ void gemm_phase(LAS unsigned char* lds, const int tid, const Gemm g, const Sched& S, const Epi& E) {
;     ...
;             PG8_LDB(B0, 1, 0); PG8_LDB(B1, 1, 1); PG8_SCHED; PG8_LDA(At, 1, 0); PG8_STAGE(PG8_SA(0, 1), a2 + hstep, voffA);
;             PG8_WAIT_V(8); PG8_WAIT_L(0); PG8_BAR; PG8_MMA(0, 0, At, B0); PG8_MMA(0, 1, At, B1); PG8_BAR; PG8_SCHED;
;             PG8_LDA(At, 1, 1); PG8_STAGE(PG8_SB(1, 0), b3, voffB); PG8_STAGE(PG8_SB(1, 1), b3 + hstep, voffB); PG8_STAGE(PG8_SA(1, 0), a3, voffA);
;             PG8_WAIT_V(8); PG8_WAIT_L(0); PG8_BAR; PG8_MMA(1, 0, At, B0); PG8_MMA(1, 1, At, B1); PG8_BAR; PG8_SCHED;
;         }
	s_setprio 0
	s_add_i32 s44, 0, 0x18000
	s_add_i32 s45, 0, 0x1c000
	v_add_u32_e32 v158, s44, v143
	v_add_u32_e32 v174, s45, v143
	ds_read_b128 v[146:149], v158
	ds_read_b128 v[150:153], v158 offset:1024
	ds_read_b128 v[154:157], v158 offset:2048
	ds_read_b128 v[158:161], v158 offset:3072
	ds_read_b128 v[162:165], v174
	ds_read_b128 v[166:169], v174 offset:1024
	ds_read_b128 v[170:173], v174 offset:2048
	ds_read_b128 v[174:177], v174 offset:3072
	s_add_u32 s42, s60, 0x40000
	s_addc_u32 s43, s61, 0
	s_mov_b32 m0, s29
	ds_read_b128 v[178:181], v145 offset:32768
	ds_read_b128 v[182:185], v145 offset:33792
	ds_read_b128 v[186:189], v145 offset:34816
	ds_read_b128 v[190:193], v145 offset:35840
	ds_read_b128 v[204:207], v145 offset:36864
	ds_read_b128 v[208:211], v145 offset:37888
	ds_read_b128 v[212:215], v145 offset:38912
	ds_read_b128 v[216:219], v145 offset:39936
	global_load_lds_dwordx4 v134, s[42:43]
	s_mov_b32 m0, s30
	s_nop 0
	global_load_lds_dwordx4 v132, s[42:43]
	s_waitcnt vmcnt(8)
	s_waitcnt lgkmcnt(0)
	s_barrier
	s_setprio 1
	v_mfma_f32_16x16x32_bf16 v[126:129], v[146:149], v[178:181], v[126:129]
	v_mfma_f32_16x16x32_bf16 v[122:125], v[154:157], v[178:181], v[122:125]
	v_mfma_f32_16x16x32_bf16 v[110:113], v[146:149], v[186:189], v[110:113]
	v_mfma_f32_16x16x32_bf16 v[106:109], v[154:157], v[186:189], v[106:109]
	v_mfma_f32_16x16x32_bf16 v[94:97], v[146:149], v[204:207], v[94:97]
	v_mfma_f32_16x16x32_bf16 v[90:93], v[154:157], v[204:207], v[90:93]
	v_mfma_f32_16x16x32_bf16 v[78:81], v[146:149], v[212:215], v[78:81]
	v_mfma_f32_16x16x32_bf16 v[74:77], v[154:157], v[212:215], v[74:77]
	v_mfma_f32_16x16x32_bf16 v[126:129], v[150:153], v[182:185], v[126:129]
	v_mfma_f32_16x16x32_bf16 v[122:125], v[158:161], v[182:185], v[122:125]
	v_mfma_f32_16x16x32_bf16 v[110:113], v[150:153], v[190:193], v[110:113]
	v_mfma_f32_16x16x32_bf16 v[106:109], v[158:161], v[190:193], v[106:109]
	v_mfma_f32_16x16x32_bf16 v[94:97], v[150:153], v[208:211], v[94:97]
	v_mfma_f32_16x16x32_bf16 v[90:93], v[158:161], v[208:211], v[90:93]
	v_mfma_f32_16x16x32_bf16 v[78:81], v[150:153], v[216:219], v[78:81]
	v_mfma_f32_16x16x32_bf16 v[74:77], v[158:161], v[216:219], v[74:77]
	v_mfma_f32_16x16x32_bf16 v[118:121], v[162:165], v[178:181], v[118:121]
	v_mfma_f32_16x16x32_bf16 v[114:117], v[170:173], v[178:181], v[114:117]
	v_mfma_f32_16x16x32_bf16 v[102:105], v[162:165], v[186:189], v[102:105]
	v_mfma_f32_16x16x32_bf16 v[98:101], v[170:173], v[186:189], v[98:101]
	v_mfma_f32_16x16x32_bf16 v[86:89], v[162:165], v[204:207], v[86:89]
	v_mfma_f32_16x16x32_bf16 v[82:85], v[170:173], v[204:207], v[82:85]
	v_mfma_f32_16x16x32_bf16 v[70:73], v[162:165], v[212:215], v[70:73]
	v_mfma_f32_16x16x32_bf16 v[66:69], v[170:173], v[212:215], v[66:69]
	v_mfma_f32_16x16x32_bf16 v[118:121], v[166:169], v[182:185], v[118:121]
	v_mfma_f32_16x16x32_bf16 v[114:117], v[174:177], v[182:185], v[114:117]
	v_mfma_f32_16x16x32_bf16 v[102:105], v[166:169], v[190:193], v[102:105]
	v_mfma_f32_16x16x32_bf16 v[98:101], v[174:177], v[190:193], v[98:101]
	v_mfma_f32_16x16x32_bf16 v[86:89], v[166:169], v[208:211], v[86:89]
	v_mfma_f32_16x16x32_bf16 v[82:85], v[174:177], v[208:211], v[82:85]
	v_mfma_f32_16x16x32_bf16 v[70:73], v[166:169], v[216:219], v[70:73]
	v_mfma_f32_16x16x32_bf16 v[66:69], v[174:177], v[216:219], v[66:69]
	s_barrier
	s_setprio 0
	s_add_i32 s42, s44, s12
	s_mov_b32 m0, s42
	ds_read_b128 v[178:181], v145 offset:49152
	ds_read_b128 v[182:185], v145 offset:50176
	ds_read_b128 v[186:189], v145 offset:51200
	ds_read_b128 v[190:193], v145 offset:52224
	ds_read_b128 v[204:207], v145 offset:53248
	ds_read_b128 v[208:211], v145 offset:54272
	ds_read_b128 v[212:215], v145 offset:55296
	ds_read_b128 v[216:219], v145 offset:56320
	global_load_lds_dwordx4 v141, s[20:21]
	s_add_i32 m0, s42, 0x2000
	s_add_i32 s42, s45, s12
	global_load_lds_dwordx4 v195, s[20:21]
	s_add_u32 s20, s20, 0x40080
	s_addc_u32 s21, s21, 0
	s_mov_b32 m0, s42
	s_nop 0
	global_load_lds_dwordx4 v0, s[20:21]
	s_add_i32 m0, s42, 0x2000
	s_nop 0
	global_load_lds_dwordx4 v130, s[20:21]
	s_mov_b32 m0, s31
	s_nop 0
	global_load_lds_dwordx4 v221, s[60:61]
	s_mov_b32 m0, s34
	s_nop 0
	global_load_lds_dwordx4 v223, s[60:61]
	s_waitcnt vmcnt(8)
	s_waitcnt lgkmcnt(0)
	s_barrier
	s_setprio 1
	v_mfma_f32_16x16x32_bf16 v[62:65], v[146:149], v[178:181], v[62:65]
	v_mfma_f32_16x16x32_bf16 v[58:61], v[154:157], v[178:181], v[58:61]
	v_mfma_f32_16x16x32_bf16 v[46:49], v[146:149], v[186:189], v[46:49]
	v_mfma_f32_16x16x32_bf16 v[42:45], v[154:157], v[186:189], v[42:45]
	v_mfma_f32_16x16x32_bf16 v[30:33], v[146:149], v[204:207], v[30:33]
	v_mfma_f32_16x16x32_bf16 v[26:29], v[154:157], v[204:207], v[26:29]
	v_mfma_f32_16x16x32_bf16 v[14:17], v[146:149], v[212:215], v[14:17]
	v_mfma_f32_16x16x32_bf16 v[10:13], v[154:157], v[212:215], v[10:13]
	v_mfma_f32_16x16x32_bf16 v[62:65], v[150:153], v[182:185], v[62:65]
	v_mfma_f32_16x16x32_bf16 v[58:61], v[158:161], v[182:185], v[58:61]
	v_mfma_f32_16x16x32_bf16 v[46:49], v[150:153], v[190:193], v[46:49]
	v_mfma_f32_16x16x32_bf16 v[42:45], v[158:161], v[190:193], v[42:45]
	v_mfma_f32_16x16x32_bf16 v[30:33], v[150:153], v[208:211], v[30:33]
	v_mfma_f32_16x16x32_bf16 v[26:29], v[158:161], v[208:211], v[26:29]
	v_mfma_f32_16x16x32_bf16 v[14:17], v[150:153], v[216:219], v[14:17]
	v_mfma_f32_16x16x32_bf16 v[10:13], v[158:161], v[216:219], v[10:13]
	v_mfma_f32_16x16x32_bf16 v[54:57], v[162:165], v[178:181], v[54:57]
	v_mfma_f32_16x16x32_bf16 v[50:53], v[170:173], v[178:181], v[50:53]
	v_mfma_f32_16x16x32_bf16 v[38:41], v[162:165], v[186:189], v[38:41]
	v_mfma_f32_16x16x32_bf16 v[34:37], v[170:173], v[186:189], v[34:37]
	v_mfma_f32_16x16x32_bf16 v[22:25], v[162:165], v[204:207], v[22:25]
	v_mfma_f32_16x16x32_bf16 v[18:21], v[170:173], v[204:207], v[18:21]
	v_mfma_f32_16x16x32_bf16 v[6:9], v[162:165], v[212:215], v[6:9]
	v_mfma_f32_16x16x32_bf16 v[2:5], v[170:173], v[212:215], v[2:5]
	v_mfma_f32_16x16x32_bf16 v[54:57], v[166:169], v[182:185], v[54:57]
	v_mfma_f32_16x16x32_bf16 v[50:53], v[174:177], v[182:185], v[50:53]
	v_mfma_f32_16x16x32_bf16 v[38:41], v[166:169], v[190:193], v[38:41]
	v_mfma_f32_16x16x32_bf16 v[34:37], v[174:177], v[190:193], v[34:37]
	v_mfma_f32_16x16x32_bf16 v[22:25], v[166:169], v[208:211], v[22:25]
	v_mfma_f32_16x16x32_bf16 v[18:21], v[174:177], v[208:211], v[18:21]
	v_mfma_f32_16x16x32_bf16 v[6:9], v[166:169], v[216:219], v[6:9]
	v_mfma_f32_16x16x32_bf16 v[2:5], v[174:177], v[216:219], v[2:5]
	s_barrier
	s_setprio 0
	s_add_i32 s41, s41, 2
	s_add_u32 s39, s39, 0x100
	s_addc_u32 s40, s40, 0
	s_add_u32 s58, s58, 0x100
	s_addc_u32 s59, s59, 0
	s_cmp_gt_u32 s41, 13
	s_cbranch_scc0 .LBB0_647
	s_and_b64 vcc, exec, s[4:5]
	s_cbranch_vccz .LBB0_650
	s_barrier
